# v18 + GEMM unit preheader vmcnt(0) dropped, NORM n=0 serialized x-load waits removed, sample_gemm LDS reduce reads pipelined
# speedup vs baseline: 1.0168x; 1.0011x over previous
; DI unsigned pk2(float lo, float hi) { f32x2 v = {lo, hi}; bf16x2_t b = __builtin_convertvector(v, bf16x2_t); return __builtin_bit_cast(unsigned, b); }
; DI float fexp2(float x) { return __builtin_amdgcn_exp2f(x); }
; DI float frcp(float x) { return __builtin_amdgcn_rcpf(x); }
; DI int crow(int i, int h) { return (i & 3) + 8 * (i >> 2) + 4 * h; }
; DI void sample_gemm(ArgsP AP0, LAS unsigned char* lds, const pg8::Gemm g, int mode, int l) {
;     ...
;             for (int i = 0; i < 16; ++i) {
;                 float v = acc[i];
; #pragma unroll
;                 for (int w = 0; w < 7; ++w) v += red[(w * 16 + i) * 64 + lane];
;                 const int rr = 32 * wm + crow(i, h), row = RP + rr, bs = rr >> 4, s = rr & 15;
;                 if (mode == 1) { const float t = 0.7978845608028654f * (v + 0.044715f * v * v * v); v = v * frcp(1.f + fexp2(-2.f * LOG2E * t)); }
;                 else if (mode == 2 || mode == 3) {
;                     const int region = col >> 10;
;                     if (mode == 2 && region < 2 && (n0 & 32) == 0) {
;                         const float pv = __shfl_xor(v, 8);
;                         if (r32 < 16) { const f32x2 cs = *(const f32x2*)((const float*)(ws + WS_ROPE) + (size_t)(2048 + s) * 16 + 2 * (r32 & 7)); v = v * cs[0] + ((r32 < 8) ? -pv : pv) * cs[1]; }
;                     }
;                     if (region == 0) v *= (mode == 2) ? QSCALE_DIFF : QSCALE_SB;
;                     else { const int kc = col & 1023;
;                         float* dst = outp + (region == 1 ? (mode == 2 ? O_DKS : O_SKS) : (mode == 2 ? O_DVS : O_SVS)) + (size_t)rr * DM + kc; *dst = v;
;                         bf16* cd = (bf16*)(ws + WS_BIG + 4 * U1 + (region == 1 ? 0 : CACHE_B)) + ((size_t)bs * CROWS + 2048 + s) * DM + kc; *cd = (bf16)(pk2(v, 0.f) & 0xffffu); }
;                 } else if (mode == 4) {
;                     const int tl = col >> 8, j = col & 255, chn = tl * 128 + (j & 127); const bool isg = j < 128;
;                     if (isg && s >= SSEQ - 2) outp[O_FS + (size_t)l * NBS * 2 * DFF + ((size_t)bs * 2 + (s - (SSEQ - 2))) * DFF + chn] = v;
;                     ((bf16*)(ws + WS_SGU))[(size_t)rr * 5632 + (isg ? chn : DFF + chn)] = (bf16)(pk2(v, 0.f) & 0xffffu);
.LBB0_350:
	ds_read2st64_b32 v[142:143], v150 offset0:1 offset1:17
	ds_read2st64_b32 v[236:237], v150 offset0:33 offset1:49
	ds_read2st64_b32 v[238:239], v150 offset0:65 offset1:81
	ds_read_b32 v240, v150 offset:24832
	v_or_b32_e32 v141, s84, v173
	s_mov_b64 s[2:3], -1
	s_andn2_b64 vcc, exec, s[18:19]
	s_waitcnt lgkmcnt(3)
	v_add_f32_e32 v0, v1, v142
	v_add_f32_e32 v96, v0, v143
	s_waitcnt lgkmcnt(2)
	v_add_f32_e32 v0, v96, v236
	v_add_f32_e32 v96, v0, v237
	s_waitcnt lgkmcnt(1)
	v_add_f32_e32 v0, v96, v238
	v_add_f32_e32 v0, v0, v239
	s_waitcnt lgkmcnt(0)
	v_add_f32_e32 v0, v0, v240
	v_cndmask_b32_e64 v1, 0, 1, s[18:19]
	v_cmp_ne_u32_e64 s[58:59], 1, v1
	v_cndmask_b32_e64 v1, 0, 1, s[20:21]
	v_cmp_ne_u32_e64 s[56:57], 1, v1
	s_cbranch_vccnz .LBB0_582
	s_and_b64 vcc, exec, s[56:57]
	s_cbranch_vccnz .LBB0_355
	s_andn2_b64 vcc, exec, s[16:17]
	s_cbranch_vccnz .LBB0_354
	v_mul_u32_u24_e32 v96, 0x2c00, v141
	v_lshl_add_u64 v[142:143], v[102:103], 0, v[96:97]
	v_cvt_pk_bf16_f32 v1, v0, s0
	global_store_short v[142:143], v1, off

; DI unsigned pk2(float lo, float hi) { f32x2 v = {lo, hi}; bf16x2_t b = __builtin_convertvector(v, bf16x2_t); return __builtin_bit_cast(unsigned, b); }
; DI float fexp2(float x) { return __builtin_amdgcn_exp2f(x); }
; DI float frcp(float x) { return __builtin_amdgcn_rcpf(x); }
; DI int crow(int i, int h) { return (i & 3) + 8 * (i >> 2) + 4 * h; }
; DI void sample_gemm(ArgsP AP0, LAS unsigned char* lds, const pg8::Gemm g, int mode, int l) {
;     ...
;             for (int i = 0; i < 16; ++i) {
;                 float v = acc[i];
; #pragma unroll
;                 for (int w = 0; w < 7; ++w) v += red[(w * 16 + i) * 64 + lane];
;                 const int rr = 32 * wm + crow(i, h), row = RP + rr, bs = rr >> 4, s = rr & 15;
;                 if (mode == 1) { const float t = 0.7978845608028654f * (v + 0.044715f * v * v * v); v = v * frcp(1.f + fexp2(-2.f * LOG2E * t)); }
;                 else if (mode == 2 || mode == 3) {
;                     const int region = col >> 10;
;                     if (mode == 2 && region < 2 && (n0 & 32) == 0) {
;                         const float pv = __shfl_xor(v, 8);
;                         if (r32 < 16) { const f32x2 cs = *(const f32x2*)((const float*)(ws + WS_ROPE) + (size_t)(2048 + s) * 16 + 2 * (r32 & 7)); v = v * cs[0] + ((r32 < 8) ? -pv : pv) * cs[1]; }
;                     }
;                     if (region == 0) v *= (mode == 2) ? QSCALE_DIFF : QSCALE_SB;
;                     else { const int kc = col & 1023;
;                         float* dst = outp + (region == 1 ? (mode == 2 ? O_DKS : O_SKS) : (mode == 2 ? O_DVS : O_SVS)) + (size_t)rr * DM + kc; *dst = v;
;                         bf16* cd = (bf16*)(ws + WS_BIG + 4 * U1 + (region == 1 ? 0 : CACHE_B)) + ((size_t)bs * CROWS + 2048 + s) * DM + kc; *cd = (bf16)(pk2(v, 0.f) & 0xffffu); }
;                 } else if (mode == 4) {
;                     const int tl = col >> 8, j = col & 255, chn = tl * 128 + (j & 127); const bool isg = j < 128;
;                     if (isg && s >= SSEQ - 2) outp[O_FS + (size_t)l * NBS * 2 * DFF + ((size_t)bs * 2 + (s - (SSEQ - 2))) * DFF + chn] = v;
;                     ((bf16*)(ws + WS_SGU))[(size_t)rr * 5632 + (isg ? chn : DFF + chn)] = (bf16)(pk2(v, 0.f) & 0xffffu);
.LBB0_365:
	ds_read2st64_b32 v[0:1], v150 offset0:2 offset1:18
	ds_read2st64_b32 v[236:237], v150 offset0:34 offset1:50
	ds_read2st64_b32 v[238:239], v150 offset0:66 offset1:82
	ds_read_b32 v240, v150 offset:25088
	s_mov_b64 s[2:3], -1
	s_and_b64 vcc, exec, s[58:59]
	s_waitcnt lgkmcnt(3)
	v_add_f32_e32 v0, v2, v0
	v_add_f32_e32 v2, v0, v1
	s_waitcnt lgkmcnt(2)
	v_add_f32_e32 v0, v2, v236
	v_add_f32_e32 v2, v0, v237
	s_waitcnt lgkmcnt(1)
	v_add_f32_e32 v0, v2, v238
	v_add_f32_e32 v0, v0, v239
	v_or_b32_e32 v2, s84, v174
	s_waitcnt lgkmcnt(0)
	v_add_f32_e32 v0, v0, v240
	s_cbranch_vccnz .LBB0_584
	s_and_b64 vcc, exec, s[56:57]
	s_cbranch_vccnz .LBB0_370
	s_andn2_b64 vcc, exec, s[16:17]
	s_cbranch_vccnz .LBB0_369
	v_mul_u32_u24_e32 v96, 0x2c00, v2
	v_lshl_add_u64 v[142:143], v[102:103], 0, v[96:97]
	v_cvt_pk_bf16_f32 v1, v0, s0
	global_store_short v[142:143], v1, off

; DI unsigned pk2(float lo, float hi) { f32x2 v = {lo, hi}; bf16x2_t b = __builtin_convertvector(v, bf16x2_t); return __builtin_bit_cast(unsigned, b); }
; DI float fexp2(float x) { return __builtin_amdgcn_exp2f(x); }
; DI float frcp(float x) { return __builtin_amdgcn_rcpf(x); }
; DI int crow(int i, int h) { return (i & 3) + 8 * (i >> 2) + 4 * h; }
; DI void sample_gemm(ArgsP AP0, LAS unsigned char* lds, const pg8::Gemm g, int mode, int l) {
;     ...
;             for (int i = 0; i < 16; ++i) {
;                 float v = acc[i];
; #pragma unroll
;                 for (int w = 0; w < 7; ++w) v += red[(w * 16 + i) * 64 + lane];
;                 const int rr = 32 * wm + crow(i, h), row = RP + rr, bs = rr >> 4, s = rr & 15;
;                 if (mode == 1) { const float t = 0.7978845608028654f * (v + 0.044715f * v * v * v); v = v * frcp(1.f + fexp2(-2.f * LOG2E * t)); }
;                 else if (mode == 2 || mode == 3) {
;                     const int region = col >> 10;
;                     if (mode == 2 && region < 2 && (n0 & 32) == 0) {
;                         const float pv = __shfl_xor(v, 8);
;                         if (r32 < 16) { const f32x2 cs = *(const f32x2*)((const float*)(ws + WS_ROPE) + (size_t)(2048 + s) * 16 + 2 * (r32 & 7)); v = v * cs[0] + ((r32 < 8) ? -pv : pv) * cs[1]; }
;                     }
;                     if (region == 0) v *= (mode == 2) ? QSCALE_DIFF : QSCALE_SB;
;                     else { const int kc = col & 1023;
;                         float* dst = outp + (region == 1 ? (mode == 2 ? O_DKS : O_SKS) : (mode == 2 ? O_DVS : O_SVS)) + (size_t)rr * DM + kc; *dst = v;
;                         bf16* cd = (bf16*)(ws + WS_BIG + 4 * U1 + (region == 1 ? 0 : CACHE_B)) + ((size_t)bs * CROWS + 2048 + s) * DM + kc; *cd = (bf16)(pk2(v, 0.f) & 0xffffu); }
;                 } else if (mode == 4) {
;                     const int tl = col >> 8, j = col & 255, chn = tl * 128 + (j & 127); const bool isg = j < 128;
;                     if (isg && s >= SSEQ - 2) outp[O_FS + (size_t)l * NBS * 2 * DFF + ((size_t)bs * 2 + (s - (SSEQ - 2))) * DFF + chn] = v;
;                     ((bf16*)(ws + WS_SGU))[(size_t)rr * 5632 + (isg ? chn : DFF + chn)] = (bf16)(pk2(v, 0.f) & 0xffffu);
.LBB0_380:
	ds_read2st64_b32 v[0:1], v150 offset0:3 offset1:19
	ds_read2st64_b32 v[236:237], v150 offset0:35 offset1:51
	ds_read2st64_b32 v[238:239], v150 offset0:67 offset1:83
	ds_read_b32 v240, v150 offset:25344
	s_mov_b64 s[2:3], -1
	s_and_b64 vcc, exec, s[58:59]
	s_waitcnt lgkmcnt(3)
	v_add_f32_e32 v0, v3, v0
	v_add_f32_e32 v2, v0, v1
	s_waitcnt lgkmcnt(2)
	v_add_f32_e32 v0, v2, v236
	v_add_f32_e32 v2, v0, v237
	s_waitcnt lgkmcnt(1)
	v_add_f32_e32 v0, v2, v238
	v_add_f32_e32 v0, v0, v239
	v_or_b32_e32 v2, s84, v175
	s_waitcnt lgkmcnt(0)
	v_add_f32_e32 v0, v0, v240
	s_cbranch_vccnz .LBB0_586
	s_and_b64 vcc, exec, s[56:57]
	s_cbranch_vccnz .LBB0_385
	s_andn2_b64 vcc, exec, s[16:17]
	s_cbranch_vccnz .LBB0_384
	v_mul_u32_u24_e32 v96, 0x2c00, v2
	v_lshl_add_u64 v[142:143], v[102:103], 0, v[96:97]
	v_cvt_pk_bf16_f32 v1, v0, s0
	global_store_short v[142:143], v1, off

; DI unsigned pk2(float lo, float hi) { f32x2 v = {lo, hi}; bf16x2_t b = __builtin_convertvector(v, bf16x2_t); return __builtin_bit_cast(unsigned, b); }
; DI float fexp2(float x) { return __builtin_amdgcn_exp2f(x); }
; DI float frcp(float x) { return __builtin_amdgcn_rcpf(x); }
; DI int crow(int i, int h) { return (i & 3) + 8 * (i >> 2) + 4 * h; }
; DI void sample_gemm(ArgsP AP0, LAS unsigned char* lds, const pg8::Gemm g, int mode, int l) {
;     ...
;             for (int i = 0; i < 16; ++i) {
;                 float v = acc[i];
; #pragma unroll
;                 for (int w = 0; w < 7; ++w) v += red[(w * 16 + i) * 64 + lane];
;                 const int rr = 32 * wm + crow(i, h), row = RP + rr, bs = rr >> 4, s = rr & 15;
;                 if (mode == 1) { const float t = 0.7978845608028654f * (v + 0.044715f * v * v * v); v = v * frcp(1.f + fexp2(-2.f * LOG2E * t)); }
;                 else if (mode == 2 || mode == 3) {
;                     const int region = col >> 10;
;                     if (mode == 2 && region < 2 && (n0 & 32) == 0) {
;                         const float pv = __shfl_xor(v, 8);
;                         if (r32 < 16) { const f32x2 cs = *(const f32x2*)((const float*)(ws + WS_ROPE) + (size_t)(2048 + s) * 16 + 2 * (r32 & 7)); v = v * cs[0] + ((r32 < 8) ? -pv : pv) * cs[1]; }
;                     }
;                     if (region == 0) v *= (mode == 2) ? QSCALE_DIFF : QSCALE_SB;
;                     else { const int kc = col & 1023;
;                         float* dst = outp + (region == 1 ? (mode == 2 ? O_DKS : O_SKS) : (mode == 2 ? O_DVS : O_SVS)) + (size_t)rr * DM + kc; *dst = v;
;                         bf16* cd = (bf16*)(ws + WS_BIG + 4 * U1 + (region == 1 ? 0 : CACHE_B)) + ((size_t)bs * CROWS + 2048 + s) * DM + kc; *cd = (bf16)(pk2(v, 0.f) & 0xffffu); }
;                 } else if (mode == 4) {
;                     const int tl = col >> 8, j = col & 255, chn = tl * 128 + (j & 127); const bool isg = j < 128;
;                     if (isg && s >= SSEQ - 2) outp[O_FS + (size_t)l * NBS * 2 * DFF + ((size_t)bs * 2 + (s - (SSEQ - 2))) * DFF + chn] = v;
;                     ((bf16*)(ws + WS_SGU))[(size_t)rr * 5632 + (isg ? chn : DFF + chn)] = (bf16)(pk2(v, 0.f) & 0xffffu);
.LBB0_395:
	ds_read2st64_b32 v[0:1], v150 offset0:4 offset1:20
	ds_read2st64_b32 v[236:237], v150 offset0:36 offset1:52
	ds_read2st64_b32 v[238:239], v150 offset0:68 offset1:84
	ds_read_b32 v240, v150 offset:25600
	s_mov_b64 s[2:3], -1
	s_and_b64 vcc, exec, s[58:59]
	s_waitcnt lgkmcnt(3)
	v_add_f32_e32 v0, v4, v0
	v_add_f32_e32 v2, v0, v1
	s_waitcnt lgkmcnt(2)
	v_add_f32_e32 v0, v2, v236
	v_add_f32_e32 v2, v0, v237
	s_waitcnt lgkmcnt(1)
	v_add_f32_e32 v0, v2, v238
	v_add_f32_e32 v0, v0, v239
	v_or_b32_e32 v2, s84, v176
	s_waitcnt lgkmcnt(0)
	v_add_f32_e32 v0, v0, v240
	s_cbranch_vccnz .LBB0_588
	s_and_b64 vcc, exec, s[56:57]
	s_cbranch_vccnz .LBB0_400
	s_andn2_b64 vcc, exec, s[16:17]
	s_cbranch_vccnz .LBB0_399
	v_mul_u32_u24_e32 v96, 0x2c00, v2
	v_lshl_add_u64 v[142:143], v[102:103], 0, v[96:97]
	v_cvt_pk_bf16_f32 v1, v0, s0
	global_store_short v[142:143], v1, off

; DI unsigned pk2(float lo, float hi) { f32x2 v = {lo, hi}; bf16x2_t b = __builtin_convertvector(v, bf16x2_t); return __builtin_bit_cast(unsigned, b); }
; DI float fexp2(float x) { return __builtin_amdgcn_exp2f(x); }
; DI float frcp(float x) { return __builtin_amdgcn_rcpf(x); }
; DI int crow(int i, int h) { return (i & 3) + 8 * (i >> 2) + 4 * h; }
; DI void sample_gemm(ArgsP AP0, LAS unsigned char* lds, const pg8::Gemm g, int mode, int l) {
;     ...
;             for (int i = 0; i < 16; ++i) {
;                 float v = acc[i];
; #pragma unroll
;                 for (int w = 0; w < 7; ++w) v += red[(w * 16 + i) * 64 + lane];
;                 const int rr = 32 * wm + crow(i, h), row = RP + rr, bs = rr >> 4, s = rr & 15;
;                 if (mode == 1) { const float t = 0.7978845608028654f * (v + 0.044715f * v * v * v); v = v * frcp(1.f + fexp2(-2.f * LOG2E * t)); }
;                 else if (mode == 2 || mode == 3) {
;                     const int region = col >> 10;
;                     if (mode == 2 && region < 2 && (n0 & 32) == 0) {
;                         const float pv = __shfl_xor(v, 8);
;                         if (r32 < 16) { const f32x2 cs = *(const f32x2*)((const float*)(ws + WS_ROPE) + (size_t)(2048 + s) * 16 + 2 * (r32 & 7)); v = v * cs[0] + ((r32 < 8) ? -pv : pv) * cs[1]; }
;                     }
;                     if (region == 0) v *= (mode == 2) ? QSCALE_DIFF : QSCALE_SB;
;                     else { const int kc = col & 1023;
;                         float* dst = outp + (region == 1 ? (mode == 2 ? O_DKS : O_SKS) : (mode == 2 ? O_DVS : O_SVS)) + (size_t)rr * DM + kc; *dst = v;
;                         bf16* cd = (bf16*)(ws + WS_BIG + 4 * U1 + (region == 1 ? 0 : CACHE_B)) + ((size_t)bs * CROWS + 2048 + s) * DM + kc; *cd = (bf16)(pk2(v, 0.f) & 0xffffu); }
;                 } else if (mode == 4) {
;                     const int tl = col >> 8, j = col & 255, chn = tl * 128 + (j & 127); const bool isg = j < 128;
;                     if (isg && s >= SSEQ - 2) outp[O_FS + (size_t)l * NBS * 2 * DFF + ((size_t)bs * 2 + (s - (SSEQ - 2))) * DFF + chn] = v;
;                     ((bf16*)(ws + WS_SGU))[(size_t)rr * 5632 + (isg ? chn : DFF + chn)] = (bf16)(pk2(v, 0.f) & 0xffffu);
.LBB0_410:
	ds_read2st64_b32 v[0:1], v150 offset0:5 offset1:21
	ds_read2st64_b32 v[236:237], v150 offset0:37 offset1:53
	ds_read2st64_b32 v[238:239], v150 offset0:69 offset1:85
	ds_read_b32 v240, v150 offset:25856
	s_mov_b64 s[2:3], -1
	s_and_b64 vcc, exec, s[58:59]
	s_waitcnt lgkmcnt(3)
	v_add_f32_e32 v0, v5, v0
	v_add_f32_e32 v2, v0, v1
	s_waitcnt lgkmcnt(2)
	v_add_f32_e32 v0, v2, v236
	v_add_f32_e32 v2, v0, v237
	s_waitcnt lgkmcnt(1)
	v_add_f32_e32 v0, v2, v238
	v_add_f32_e32 v0, v0, v239
	v_or_b32_e32 v2, s84, v177
	s_waitcnt lgkmcnt(0)
	v_add_f32_e32 v0, v0, v240
	s_cbranch_vccnz .LBB0_590
	s_and_b64 vcc, exec, s[56:57]
	s_cbranch_vccnz .LBB0_415
	s_andn2_b64 vcc, exec, s[16:17]
	s_cbranch_vccnz .LBB0_414
	v_mul_u32_u24_e32 v96, 0x2c00, v2
	v_lshl_add_u64 v[4:5], v[102:103], 0, v[96:97]
	v_cvt_pk_bf16_f32 v1, v0, s0
	global_store_short v[4:5], v1, off

; DI unsigned pk2(float lo, float hi) { f32x2 v = {lo, hi}; bf16x2_t b = __builtin_convertvector(v, bf16x2_t); return __builtin_bit_cast(unsigned, b); }
; DI float fexp2(float x) { return __builtin_amdgcn_exp2f(x); }
; DI float frcp(float x) { return __builtin_amdgcn_rcpf(x); }
; DI int crow(int i, int h) { return (i & 3) + 8 * (i >> 2) + 4 * h; }
; DI void sample_gemm(ArgsP AP0, LAS unsigned char* lds, const pg8::Gemm g, int mode, int l) {
;     ...
;             for (int i = 0; i < 16; ++i) {
;                 float v = acc[i];
; #pragma unroll
;                 for (int w = 0; w < 7; ++w) v += red[(w * 16 + i) * 64 + lane];
;                 const int rr = 32 * wm + crow(i, h), row = RP + rr, bs = rr >> 4, s = rr & 15;
;                 if (mode == 1) { const float t = 0.7978845608028654f * (v + 0.044715f * v * v * v); v = v * frcp(1.f + fexp2(-2.f * LOG2E * t)); }
;                 else if (mode == 2 || mode == 3) {
;                     const int region = col >> 10;
;                     if (mode == 2 && region < 2 && (n0 & 32) == 0) {
;                         const float pv = __shfl_xor(v, 8);
;                         if (r32 < 16) { const f32x2 cs = *(const f32x2*)((const float*)(ws + WS_ROPE) + (size_t)(2048 + s) * 16 + 2 * (r32 & 7)); v = v * cs[0] + ((r32 < 8) ? -pv : pv) * cs[1]; }
;                     }
;                     if (region == 0) v *= (mode == 2) ? QSCALE_DIFF : QSCALE_SB;
;                     else { const int kc = col & 1023;
;                         float* dst = outp + (region == 1 ? (mode == 2 ? O_DKS : O_SKS) : (mode == 2 ? O_DVS : O_SVS)) + (size_t)rr * DM + kc; *dst = v;
;                         bf16* cd = (bf16*)(ws + WS_BIG + 4 * U1 + (region == 1 ? 0 : CACHE_B)) + ((size_t)bs * CROWS + 2048 + s) * DM + kc; *cd = (bf16)(pk2(v, 0.f) & 0xffffu); }
;                 } else if (mode == 4) {
;                     const int tl = col >> 8, j = col & 255, chn = tl * 128 + (j & 127); const bool isg = j < 128;
;                     if (isg && s >= SSEQ - 2) outp[O_FS + (size_t)l * NBS * 2 * DFF + ((size_t)bs * 2 + (s - (SSEQ - 2))) * DFF + chn] = v;
;                     ((bf16*)(ws + WS_SGU))[(size_t)rr * 5632 + (isg ? chn : DFF + chn)] = (bf16)(pk2(v, 0.f) & 0xffffu);
.LBB0_425:
	s_waitcnt lgkmcnt(0)
	ds_read2st64_b32 v[2:3], v150 offset0:6 offset1:22
	ds_read2st64_b32 v[236:237], v150 offset0:38 offset1:54
	ds_read2st64_b32 v[238:239], v150 offset0:70 offset1:86
	ds_read_b32 v240, v150 offset:26112
	v_ashrrev_i32_e32 v141, 31, v140
	v_lshl_add_u64 v[0:1], v[140:141], 2, s[28:29]
	s_mov_b64 s[2:3], -1
	s_and_b64 vcc, exec, s[58:59]
	s_waitcnt lgkmcnt(3)
	v_add_f32_e32 v2, v6, v2
	v_add_f32_e32 v4, v2, v3
	s_waitcnt lgkmcnt(2)
	v_add_f32_e32 v2, v4, v236
	v_add_f32_e32 v4, v2, v237
	s_waitcnt lgkmcnt(1)
	v_add_f32_e32 v2, v4, v238
	v_add_f32_e32 v2, v2, v239
	v_or_b32_e32 v4, s84, v178
	s_waitcnt lgkmcnt(0)
	v_add_f32_e32 v2, v2, v240
	s_cbranch_vccnz .LBB0_592
	s_and_b64 vcc, exec, s[56:57]
	s_cbranch_vccnz .LBB0_432
	s_andn2_b64 vcc, exec, s[16:17]
	s_cbranch_vccnz .LBB0_431
	s_and_b64 s[6:7], s[52:53], s[44:45]
	s_and_saveexec_b64 s[2:3], s[6:7]
	s_cbranch_execz .LBB0_430
	s_lshr_b32 s6, s84, 3
	v_add_u32_e32 v3, s6, v179
	s_movk_i32 s6, 0x2c00
	v_mad_u64_u32 v[140:141], s[6:7], v3, s6, v[0:1]
	global_store_dword v[140:141], v2, off

; DI unsigned pk2(float lo, float hi) { f32x2 v = {lo, hi}; bf16x2_t b = __builtin_convertvector(v, bf16x2_t); return __builtin_bit_cast(unsigned, b); }
; DI float fexp2(float x) { return __builtin_amdgcn_exp2f(x); }
; DI float frcp(float x) { return __builtin_amdgcn_rcpf(x); }
; DI int crow(int i, int h) { return (i & 3) + 8 * (i >> 2) + 4 * h; }
; DI void sample_gemm(ArgsP AP0, LAS unsigned char* lds, const pg8::Gemm g, int mode, int l) {
;     ...
;             for (int i = 0; i < 16; ++i) {
;                 float v = acc[i];
; #pragma unroll
;                 for (int w = 0; w < 7; ++w) v += red[(w * 16 + i) * 64 + lane];
;                 const int rr = 32 * wm + crow(i, h), row = RP + rr, bs = rr >> 4, s = rr & 15;
;                 if (mode == 1) { const float t = 0.7978845608028654f * (v + 0.044715f * v * v * v); v = v * frcp(1.f + fexp2(-2.f * LOG2E * t)); }
;                 else if (mode == 2 || mode == 3) {
;                     const int region = col >> 10;
;                     if (mode == 2 && region < 2 && (n0 & 32) == 0) {
;                         const float pv = __shfl_xor(v, 8);
;                         if (r32 < 16) { const f32x2 cs = *(const f32x2*)((const float*)(ws + WS_ROPE) + (size_t)(2048 + s) * 16 + 2 * (r32 & 7)); v = v * cs[0] + ((r32 < 8) ? -pv : pv) * cs[1]; }
;                     }
;                     if (region == 0) v *= (mode == 2) ? QSCALE_DIFF : QSCALE_SB;
;                     else { const int kc = col & 1023;
;                         float* dst = outp + (region == 1 ? (mode == 2 ? O_DKS : O_SKS) : (mode == 2 ? O_DVS : O_SVS)) + (size_t)rr * DM + kc; *dst = v;
;                         bf16* cd = (bf16*)(ws + WS_BIG + 4 * U1 + (region == 1 ? 0 : CACHE_B)) + ((size_t)bs * CROWS + 2048 + s) * DM + kc; *cd = (bf16)(pk2(v, 0.f) & 0xffffu); }
;                 } else if (mode == 4) {
;                     const int tl = col >> 8, j = col & 255, chn = tl * 128 + (j & 127); const bool isg = j < 128;
;                     if (isg && s >= SSEQ - 2) outp[O_FS + (size_t)l * NBS * 2 * DFF + ((size_t)bs * 2 + (s - (SSEQ - 2))) * DFF + chn] = v;
;                     ((bf16*)(ws + WS_SGU))[(size_t)rr * 5632 + (isg ? chn : DFF + chn)] = (bf16)(pk2(v, 0.f) & 0xffffu);
.LBB0_442:
	ds_read2st64_b32 v[2:3], v150 offset0:7 offset1:23
	ds_read2st64_b32 v[236:237], v150 offset0:39 offset1:55
	ds_read2st64_b32 v[238:239], v150 offset0:71 offset1:87
	ds_read_b32 v240, v150 offset:26368
	s_mov_b64 s[2:3], -1
	s_and_b64 vcc, exec, s[58:59]
	s_waitcnt lgkmcnt(3)
	v_add_f32_e32 v2, v7, v2
	v_add_f32_e32 v4, v2, v3
	s_waitcnt lgkmcnt(2)
	v_add_f32_e32 v2, v4, v236
	v_add_f32_e32 v4, v2, v237
	s_waitcnt lgkmcnt(1)
	v_add_f32_e32 v2, v4, v238
	v_add_f32_e32 v2, v2, v239
	v_or_b32_e32 v4, s84, v180
	s_waitcnt lgkmcnt(0)
	v_add_f32_e32 v2, v2, v240
	s_cbranch_vccnz .LBB0_594
	s_and_b64 vcc, exec, s[56:57]
	s_cbranch_vccnz .LBB0_449
	s_andn2_b64 vcc, exec, s[16:17]
	s_cbranch_vccnz .LBB0_448
	s_and_b64 s[6:7], s[52:53], s[46:47]
	s_and_saveexec_b64 s[2:3], s[6:7]
	s_cbranch_execz .LBB0_447
	s_lshr_b32 s6, s84, 3
	v_add_u32_e32 v3, s6, v181
	s_movk_i32 s6, 0x2c00
	v_mad_u64_u32 v[6:7], s[6:7], v3, s6, v[0:1]
	global_store_dword v[6:7], v2, off

; DI unsigned pk2(float lo, float hi) { f32x2 v = {lo, hi}; bf16x2_t b = __builtin_convertvector(v, bf16x2_t); return __builtin_bit_cast(unsigned, b); }
; DI float fexp2(float x) { return __builtin_amdgcn_exp2f(x); }
; DI float frcp(float x) { return __builtin_amdgcn_rcpf(x); }
; DI int crow(int i, int h) { return (i & 3) + 8 * (i >> 2) + 4 * h; }
; DI void sample_gemm(ArgsP AP0, LAS unsigned char* lds, const pg8::Gemm g, int mode, int l) {
;     ...
;             for (int i = 0; i < 16; ++i) {
;                 float v = acc[i];
; #pragma unroll
;                 for (int w = 0; w < 7; ++w) v += red[(w * 16 + i) * 64 + lane];
;                 const int rr = 32 * wm + crow(i, h), row = RP + rr, bs = rr >> 4, s = rr & 15;
;                 if (mode == 1) { const float t = 0.7978845608028654f * (v + 0.044715f * v * v * v); v = v * frcp(1.f + fexp2(-2.f * LOG2E * t)); }
;                 else if (mode == 2 || mode == 3) {
;                     const int region = col >> 10;
;                     if (mode == 2 && region < 2 && (n0 & 32) == 0) {
;                         const float pv = __shfl_xor(v, 8);
;                         if (r32 < 16) { const f32x2 cs = *(const f32x2*)((const float*)(ws + WS_ROPE) + (size_t)(2048 + s) * 16 + 2 * (r32 & 7)); v = v * cs[0] + ((r32 < 8) ? -pv : pv) * cs[1]; }
;                     }
;                     if (region == 0) v *= (mode == 2) ? QSCALE_DIFF : QSCALE_SB;
;                     else { const int kc = col & 1023;
;                         float* dst = outp + (region == 1 ? (mode == 2 ? O_DKS : O_SKS) : (mode == 2 ? O_DVS : O_SVS)) + (size_t)rr * DM + kc; *dst = v;
;                         bf16* cd = (bf16*)(ws + WS_BIG + 4 * U1 + (region == 1 ? 0 : CACHE_B)) + ((size_t)bs * CROWS + 2048 + s) * DM + kc; *cd = (bf16)(pk2(v, 0.f) & 0xffffu); }
;                 } else if (mode == 4) {
;                     const int tl = col >> 8, j = col & 255, chn = tl * 128 + (j & 127); const bool isg = j < 128;
;                     if (isg && s >= SSEQ - 2) outp[O_FS + (size_t)l * NBS * 2 * DFF + ((size_t)bs * 2 + (s - (SSEQ - 2))) * DFF + chn] = v;
;                     ((bf16*)(ws + WS_SGU))[(size_t)rr * 5632 + (isg ? chn : DFF + chn)] = (bf16)(pk2(v, 0.f) & 0xffffu);
.LBB0_459:
	ds_read2st64_b32 v[2:3], v150 offset0:8 offset1:24
	ds_read2st64_b32 v[236:237], v150 offset0:40 offset1:56
	ds_read2st64_b32 v[238:239], v150 offset0:72 offset1:88
	ds_read_b32 v240, v150 offset:26624
	s_mov_b64 s[2:3], -1
	s_and_b64 vcc, exec, s[58:59]
	s_waitcnt lgkmcnt(3)
	v_add_f32_e32 v2, v8, v2
	v_add_f32_e32 v4, v2, v3
	s_waitcnt lgkmcnt(2)
	v_add_f32_e32 v2, v4, v236
	v_add_f32_e32 v4, v2, v237
	s_waitcnt lgkmcnt(1)
	v_add_f32_e32 v2, v4, v238
	v_add_f32_e32 v2, v2, v239
	s_waitcnt lgkmcnt(0)
	v_add_f32_e32 v2, v2, v240
	s_cbranch_vccnz .LBB0_596
	v_or_b32_e32 v4, 16, v144
	s_and_b64 vcc, exec, s[56:57]
	s_cbranch_vccnz .LBB0_464
	s_andn2_b64 vcc, exec, s[16:17]
	s_cbranch_vccnz .LBB0_463
	v_mul_u32_u24_e32 v96, 0x2c00, v4
	v_lshl_add_u64 v[6:7], v[102:103], 0, v[96:97]
	v_cvt_pk_bf16_f32 v3, v2, s0
	global_store_short v[6:7], v3, off

; DI unsigned pk2(float lo, float hi) { f32x2 v = {lo, hi}; bf16x2_t b = __builtin_convertvector(v, bf16x2_t); return __builtin_bit_cast(unsigned, b); }
; DI float fexp2(float x) { return __builtin_amdgcn_exp2f(x); }
; DI float frcp(float x) { return __builtin_amdgcn_rcpf(x); }
; DI int crow(int i, int h) { return (i & 3) + 8 * (i >> 2) + 4 * h; }
; DI void sample_gemm(ArgsP AP0, LAS unsigned char* lds, const pg8::Gemm g, int mode, int l) {
;     ...
;             for (int i = 0; i < 16; ++i) {
;                 float v = acc[i];
; #pragma unroll
;                 for (int w = 0; w < 7; ++w) v += red[(w * 16 + i) * 64 + lane];
;                 const int rr = 32 * wm + crow(i, h), row = RP + rr, bs = rr >> 4, s = rr & 15;
;                 if (mode == 1) { const float t = 0.7978845608028654f * (v + 0.044715f * v * v * v); v = v * frcp(1.f + fexp2(-2.f * LOG2E * t)); }
;                 else if (mode == 2 || mode == 3) {
;                     const int region = col >> 10;
;                     if (mode == 2 && region < 2 && (n0 & 32) == 0) {
;                         const float pv = __shfl_xor(v, 8);
;                         if (r32 < 16) { const f32x2 cs = *(const f32x2*)((const float*)(ws + WS_ROPE) + (size_t)(2048 + s) * 16 + 2 * (r32 & 7)); v = v * cs[0] + ((r32 < 8) ? -pv : pv) * cs[1]; }
;                     }
;                     if (region == 0) v *= (mode == 2) ? QSCALE_DIFF : QSCALE_SB;
;                     else { const int kc = col & 1023;
;                         float* dst = outp + (region == 1 ? (mode == 2 ? O_DKS : O_SKS) : (mode == 2 ? O_DVS : O_SVS)) + (size_t)rr * DM + kc; *dst = v;
;                         bf16* cd = (bf16*)(ws + WS_BIG + 4 * U1 + (region == 1 ? 0 : CACHE_B)) + ((size_t)bs * CROWS + 2048 + s) * DM + kc; *cd = (bf16)(pk2(v, 0.f) & 0xffffu); }
;                 } else if (mode == 4) {
;                     const int tl = col >> 8, j = col & 255, chn = tl * 128 + (j & 127); const bool isg = j < 128;
;                     if (isg && s >= SSEQ - 2) outp[O_FS + (size_t)l * NBS * 2 * DFF + ((size_t)bs * 2 + (s - (SSEQ - 2))) * DFF + chn] = v;
;                     ((bf16*)(ws + WS_SGU))[(size_t)rr * 5632 + (isg ? chn : DFF + chn)] = (bf16)(pk2(v, 0.f) & 0xffffu);
.LBB0_474:
	ds_read2st64_b32 v[2:3], v150 offset0:9 offset1:25
	ds_read2st64_b32 v[236:237], v150 offset0:41 offset1:57
	ds_read2st64_b32 v[238:239], v150 offset0:73 offset1:89
	ds_read_b32 v240, v150 offset:26880
	s_mov_b64 s[2:3], -1
	s_and_b64 vcc, exec, s[58:59]
	s_waitcnt lgkmcnt(3)
	v_add_f32_e32 v2, v9, v2
	v_add_f32_e32 v4, v2, v3
	s_waitcnt lgkmcnt(2)
	v_add_f32_e32 v2, v4, v236
	v_add_f32_e32 v4, v2, v237
	s_waitcnt lgkmcnt(1)
	v_add_f32_e32 v2, v4, v238
	v_add_f32_e32 v2, v2, v239
	v_or_b32_e32 v4, s84, v182
	s_waitcnt lgkmcnt(0)
	v_add_f32_e32 v2, v2, v240
	s_cbranch_vccnz .LBB0_598
	s_and_b64 vcc, exec, s[56:57]
	s_cbranch_vccnz .LBB0_479
	s_andn2_b64 vcc, exec, s[16:17]
	s_cbranch_vccnz .LBB0_478
	v_mul_u32_u24_e32 v96, 0x2c00, v4
	v_lshl_add_u64 v[6:7], v[102:103], 0, v[96:97]
	v_cvt_pk_bf16_f32 v3, v2, s0
	global_store_short v[6:7], v3, off

; DI unsigned pk2(float lo, float hi) { f32x2 v = {lo, hi}; bf16x2_t b = __builtin_convertvector(v, bf16x2_t); return __builtin_bit_cast(unsigned, b); }
; DI float fexp2(float x) { return __builtin_amdgcn_exp2f(x); }
; DI float frcp(float x) { return __builtin_amdgcn_rcpf(x); }
; DI int crow(int i, int h) { return (i & 3) + 8 * (i >> 2) + 4 * h; }
; DI void sample_gemm(ArgsP AP0, LAS unsigned char* lds, const pg8::Gemm g, int mode, int l) {
;     ...
;             for (int i = 0; i < 16; ++i) {
;                 float v = acc[i];
; #pragma unroll
;                 for (int w = 0; w < 7; ++w) v += red[(w * 16 + i) * 64 + lane];
;                 const int rr = 32 * wm + crow(i, h), row = RP + rr, bs = rr >> 4, s = rr & 15;
;                 if (mode == 1) { const float t = 0.7978845608028654f * (v + 0.044715f * v * v * v); v = v * frcp(1.f + fexp2(-2.f * LOG2E * t)); }
;                 else if (mode == 2 || mode == 3) {
;                     const int region = col >> 10;
;                     if (mode == 2 && region < 2 && (n0 & 32) == 0) {
;                         const float pv = __shfl_xor(v, 8);
;                         if (r32 < 16) { const f32x2 cs = *(const f32x2*)((const float*)(ws + WS_ROPE) + (size_t)(2048 + s) * 16 + 2 * (r32 & 7)); v = v * cs[0] + ((r32 < 8) ? -pv : pv) * cs[1]; }
;                     }
;                     if (region == 0) v *= (mode == 2) ? QSCALE_DIFF : QSCALE_SB;
;                     else { const int kc = col & 1023;
;                         float* dst = outp + (region == 1 ? (mode == 2 ? O_DKS : O_SKS) : (mode == 2 ? O_DVS : O_SVS)) + (size_t)rr * DM + kc; *dst = v;
;                         bf16* cd = (bf16*)(ws + WS_BIG + 4 * U1 + (region == 1 ? 0 : CACHE_B)) + ((size_t)bs * CROWS + 2048 + s) * DM + kc; *cd = (bf16)(pk2(v, 0.f) & 0xffffu); }
;                 } else if (mode == 4) {
;                     const int tl = col >> 8, j = col & 255, chn = tl * 128 + (j & 127); const bool isg = j < 128;
;                     if (isg && s >= SSEQ - 2) outp[O_FS + (size_t)l * NBS * 2 * DFF + ((size_t)bs * 2 + (s - (SSEQ - 2))) * DFF + chn] = v;
;                     ((bf16*)(ws + WS_SGU))[(size_t)rr * 5632 + (isg ? chn : DFF + chn)] = (bf16)(pk2(v, 0.f) & 0xffffu);
.LBB0_489:
	ds_read2st64_b32 v[2:3], v150 offset0:10 offset1:26
	ds_read2st64_b32 v[236:237], v150 offset0:42 offset1:58
	ds_read2st64_b32 v[238:239], v150 offset0:74 offset1:90
	ds_read_b32 v240, v150 offset:27136
	s_mov_b64 s[2:3], -1
	s_and_b64 vcc, exec, s[58:59]
	s_waitcnt lgkmcnt(3)
	v_add_f32_e32 v2, v10, v2
	v_add_f32_e32 v4, v2, v3
	s_waitcnt lgkmcnt(2)
	v_add_f32_e32 v2, v4, v236
	v_add_f32_e32 v4, v2, v237
	s_waitcnt lgkmcnt(1)
	v_add_f32_e32 v2, v4, v238
	v_add_f32_e32 v2, v2, v239
	v_or_b32_e32 v4, s84, v183
	s_waitcnt lgkmcnt(0)
	v_add_f32_e32 v2, v2, v240
	s_cbranch_vccnz .LBB0_600
	s_and_b64 vcc, exec, s[56:57]
	s_cbranch_vccnz .LBB0_494
	s_andn2_b64 vcc, exec, s[16:17]
	s_cbranch_vccnz .LBB0_493
	v_mul_u32_u24_e32 v96, 0x2c00, v4
	v_lshl_add_u64 v[6:7], v[102:103], 0, v[96:97]
	v_cvt_pk_bf16_f32 v3, v2, s0
	global_store_short v[6:7], v3, off

; DI unsigned pk2(float lo, float hi) { f32x2 v = {lo, hi}; bf16x2_t b = __builtin_convertvector(v, bf16x2_t); return __builtin_bit_cast(unsigned, b); }
; DI float fexp2(float x) { return __builtin_amdgcn_exp2f(x); }
; DI float frcp(float x) { return __builtin_amdgcn_rcpf(x); }
; DI int crow(int i, int h) { return (i & 3) + 8 * (i >> 2) + 4 * h; }
; DI void sample_gemm(ArgsP AP0, LAS unsigned char* lds, const pg8::Gemm g, int mode, int l) {
;     ...
;             for (int i = 0; i < 16; ++i) {
;                 float v = acc[i];
; #pragma unroll
;                 for (int w = 0; w < 7; ++w) v += red[(w * 16 + i) * 64 + lane];
;                 const int rr = 32 * wm + crow(i, h), row = RP + rr, bs = rr >> 4, s = rr & 15;
;                 if (mode == 1) { const float t = 0.7978845608028654f * (v + 0.044715f * v * v * v); v = v * frcp(1.f + fexp2(-2.f * LOG2E * t)); }
;                 else if (mode == 2 || mode == 3) {
;                     const int region = col >> 10;
;                     if (mode == 2 && region < 2 && (n0 & 32) == 0) {
;                         const float pv = __shfl_xor(v, 8);
;                         if (r32 < 16) { const f32x2 cs = *(const f32x2*)((const float*)(ws + WS_ROPE) + (size_t)(2048 + s) * 16 + 2 * (r32 & 7)); v = v * cs[0] + ((r32 < 8) ? -pv : pv) * cs[1]; }
;                     }
;                     if (region == 0) v *= (mode == 2) ? QSCALE_DIFF : QSCALE_SB;
;                     else { const int kc = col & 1023;
;                         float* dst = outp + (region == 1 ? (mode == 2 ? O_DKS : O_SKS) : (mode == 2 ? O_DVS : O_SVS)) + (size_t)rr * DM + kc; *dst = v;
;                         bf16* cd = (bf16*)(ws + WS_BIG + 4 * U1 + (region == 1 ? 0 : CACHE_B)) + ((size_t)bs * CROWS + 2048 + s) * DM + kc; *cd = (bf16)(pk2(v, 0.f) & 0xffffu); }
;                 } else if (mode == 4) {
;                     const int tl = col >> 8, j = col & 255, chn = tl * 128 + (j & 127); const bool isg = j < 128;
;                     if (isg && s >= SSEQ - 2) outp[O_FS + (size_t)l * NBS * 2 * DFF + ((size_t)bs * 2 + (s - (SSEQ - 2))) * DFF + chn] = v;
;                     ((bf16*)(ws + WS_SGU))[(size_t)rr * 5632 + (isg ? chn : DFF + chn)] = (bf16)(pk2(v, 0.f) & 0xffffu);
.LBB0_504:
	ds_read2st64_b32 v[2:3], v150 offset0:11 offset1:27
	ds_read2st64_b32 v[236:237], v150 offset0:43 offset1:59
	ds_read2st64_b32 v[238:239], v150 offset0:75 offset1:91
	ds_read_b32 v240, v150 offset:27392
	s_mov_b64 s[2:3], -1
	s_and_b64 vcc, exec, s[58:59]
	s_waitcnt lgkmcnt(3)
	v_add_f32_e32 v2, v11, v2
	v_add_f32_e32 v4, v2, v3
	s_waitcnt lgkmcnt(2)
	v_add_f32_e32 v2, v4, v236
	v_add_f32_e32 v4, v2, v237
	s_waitcnt lgkmcnt(1)
	v_add_f32_e32 v2, v4, v238
	v_add_f32_e32 v2, v2, v239
	v_or_b32_e32 v4, s84, v184
	s_waitcnt lgkmcnt(0)
	v_add_f32_e32 v2, v2, v240
	s_cbranch_vccnz .LBB0_602
	s_and_b64 vcc, exec, s[56:57]
	s_cbranch_vccnz .LBB0_509
	s_andn2_b64 vcc, exec, s[16:17]
	s_cbranch_vccnz .LBB0_508
	v_mul_u32_u24_e32 v96, 0x2c00, v4
	v_lshl_add_u64 v[6:7], v[102:103], 0, v[96:97]
	v_cvt_pk_bf16_f32 v3, v2, s0
	global_store_short v[6:7], v3, off

; DI unsigned pk2(float lo, float hi) { f32x2 v = {lo, hi}; bf16x2_t b = __builtin_convertvector(v, bf16x2_t); return __builtin_bit_cast(unsigned, b); }
; DI float fexp2(float x) { return __builtin_amdgcn_exp2f(x); }
; DI float frcp(float x) { return __builtin_amdgcn_rcpf(x); }
; DI int crow(int i, int h) { return (i & 3) + 8 * (i >> 2) + 4 * h; }
; DI void sample_gemm(ArgsP AP0, LAS unsigned char* lds, const pg8::Gemm g, int mode, int l) {
;     ...
;             for (int i = 0; i < 16; ++i) {
;                 float v = acc[i];
; #pragma unroll
;                 for (int w = 0; w < 7; ++w) v += red[(w * 16 + i) * 64 + lane];
;                 const int rr = 32 * wm + crow(i, h), row = RP + rr, bs = rr >> 4, s = rr & 15;
;                 if (mode == 1) { const float t = 0.7978845608028654f * (v + 0.044715f * v * v * v); v = v * frcp(1.f + fexp2(-2.f * LOG2E * t)); }
;                 else if (mode == 2 || mode == 3) {
;                     const int region = col >> 10;
;                     if (mode == 2 && region < 2 && (n0 & 32) == 0) {
;                         const float pv = __shfl_xor(v, 8);
;                         if (r32 < 16) { const f32x2 cs = *(const f32x2*)((const float*)(ws + WS_ROPE) + (size_t)(2048 + s) * 16 + 2 * (r32 & 7)); v = v * cs[0] + ((r32 < 8) ? -pv : pv) * cs[1]; }
;                     }
;                     if (region == 0) v *= (mode == 2) ? QSCALE_DIFF : QSCALE_SB;
;                     else { const int kc = col & 1023;
;                         float* dst = outp + (region == 1 ? (mode == 2 ? O_DKS : O_SKS) : (mode == 2 ? O_DVS : O_SVS)) + (size_t)rr * DM + kc; *dst = v;
;                         bf16* cd = (bf16*)(ws + WS_BIG + 4 * U1 + (region == 1 ? 0 : CACHE_B)) + ((size_t)bs * CROWS + 2048 + s) * DM + kc; *cd = (bf16)(pk2(v, 0.f) & 0xffffu); }
;                 } else if (mode == 4) {
;                     const int tl = col >> 8, j = col & 255, chn = tl * 128 + (j & 127); const bool isg = j < 128;
;                     if (isg && s >= SSEQ - 2) outp[O_FS + (size_t)l * NBS * 2 * DFF + ((size_t)bs * 2 + (s - (SSEQ - 2))) * DFF + chn] = v;
;                     ((bf16*)(ws + WS_SGU))[(size_t)rr * 5632 + (isg ? chn : DFF + chn)] = (bf16)(pk2(v, 0.f) & 0xffffu);
.LBB0_519:
	ds_read2st64_b32 v[2:3], v150 offset0:12 offset1:28
	ds_read2st64_b32 v[236:237], v150 offset0:44 offset1:60
	ds_read2st64_b32 v[238:239], v150 offset0:76 offset1:92
	ds_read_b32 v240, v150 offset:27648
	s_mov_b64 s[2:3], -1
	s_and_b64 vcc, exec, s[58:59]
	s_waitcnt lgkmcnt(3)
	v_add_f32_e32 v2, v12, v2
	v_add_f32_e32 v4, v2, v3
	s_waitcnt lgkmcnt(2)
	v_add_f32_e32 v2, v4, v236
	v_add_f32_e32 v4, v2, v237
	s_waitcnt lgkmcnt(1)
	v_add_f32_e32 v2, v4, v238
	v_add_f32_e32 v2, v2, v239
	v_or_b32_e32 v4, s84, v185
	s_waitcnt lgkmcnt(0)
	v_add_f32_e32 v2, v2, v240
	s_cbranch_vccnz .LBB0_604
	s_and_b64 vcc, exec, s[56:57]
	s_cbranch_vccnz .LBB0_524
	s_andn2_b64 vcc, exec, s[16:17]
	s_cbranch_vccnz .LBB0_523
	v_mul_u32_u24_e32 v96, 0x2c00, v4
	v_lshl_add_u64 v[6:7], v[102:103], 0, v[96:97]
	v_cvt_pk_bf16_f32 v3, v2, s0
	global_store_short v[6:7], v3, off

; DI unsigned pk2(float lo, float hi) { f32x2 v = {lo, hi}; bf16x2_t b = __builtin_convertvector(v, bf16x2_t); return __builtin_bit_cast(unsigned, b); }
; DI float fexp2(float x) { return __builtin_amdgcn_exp2f(x); }
; DI float frcp(float x) { return __builtin_amdgcn_rcpf(x); }
; DI int crow(int i, int h) { return (i & 3) + 8 * (i >> 2) + 4 * h; }
; DI void sample_gemm(ArgsP AP0, LAS unsigned char* lds, const pg8::Gemm g, int mode, int l) {
;     ...
;             for (int i = 0; i < 16; ++i) {
;                 float v = acc[i];
; #pragma unroll
;                 for (int w = 0; w < 7; ++w) v += red[(w * 16 + i) * 64 + lane];
;                 const int rr = 32 * wm + crow(i, h), row = RP + rr, bs = rr >> 4, s = rr & 15;
;                 if (mode == 1) { const float t = 0.7978845608028654f * (v + 0.044715f * v * v * v); v = v * frcp(1.f + fexp2(-2.f * LOG2E * t)); }
;                 else if (mode == 2 || mode == 3) {
;                     const int region = col >> 10;
;                     if (mode == 2 && region < 2 && (n0 & 32) == 0) {
;                         const float pv = __shfl_xor(v, 8);
;                         if (r32 < 16) { const f32x2 cs = *(const f32x2*)((const float*)(ws + WS_ROPE) + (size_t)(2048 + s) * 16 + 2 * (r32 & 7)); v = v * cs[0] + ((r32 < 8) ? -pv : pv) * cs[1]; }
;                     }
;                     if (region == 0) v *= (mode == 2) ? QSCALE_DIFF : QSCALE_SB;
;                     else { const int kc = col & 1023;
;                         float* dst = outp + (region == 1 ? (mode == 2 ? O_DKS : O_SKS) : (mode == 2 ? O_DVS : O_SVS)) + (size_t)rr * DM + kc; *dst = v;
;                         bf16* cd = (bf16*)(ws + WS_BIG + 4 * U1 + (region == 1 ? 0 : CACHE_B)) + ((size_t)bs * CROWS + 2048 + s) * DM + kc; *cd = (bf16)(pk2(v, 0.f) & 0xffffu); }
;                 } else if (mode == 4) {
;                     const int tl = col >> 8, j = col & 255, chn = tl * 128 + (j & 127); const bool isg = j < 128;
;                     if (isg && s >= SSEQ - 2) outp[O_FS + (size_t)l * NBS * 2 * DFF + ((size_t)bs * 2 + (s - (SSEQ - 2))) * DFF + chn] = v;
;                     ((bf16*)(ws + WS_SGU))[(size_t)rr * 5632 + (isg ? chn : DFF + chn)] = (bf16)(pk2(v, 0.f) & 0xffffu);
.LBB0_534:
	ds_read2st64_b32 v[2:3], v150 offset0:13 offset1:29
	ds_read2st64_b32 v[236:237], v150 offset0:45 offset1:61
	ds_read2st64_b32 v[238:239], v150 offset0:77 offset1:93
	ds_read_b32 v240, v150 offset:27904
	s_mov_b64 s[2:3], -1
	s_and_b64 vcc, exec, s[58:59]
	s_waitcnt lgkmcnt(3)
	v_add_f32_e32 v2, v13, v2
	v_add_f32_e32 v4, v2, v3
	s_waitcnt lgkmcnt(2)
	v_add_f32_e32 v2, v4, v236
	v_add_f32_e32 v4, v2, v237
	s_waitcnt lgkmcnt(1)
	v_add_f32_e32 v2, v4, v238
	v_add_f32_e32 v2, v2, v239
	v_or_b32_e32 v4, s84, v186
	s_waitcnt lgkmcnt(0)
	v_add_f32_e32 v2, v2, v240
	s_cbranch_vccnz .LBB0_606
	s_and_b64 vcc, exec, s[56:57]
	s_cbranch_vccnz .LBB0_539
	s_andn2_b64 vcc, exec, s[16:17]
	s_cbranch_vccnz .LBB0_538
	v_mul_u32_u24_e32 v96, 0x2c00, v4
	v_lshl_add_u64 v[6:7], v[102:103], 0, v[96:97]
	v_cvt_pk_bf16_f32 v3, v2, s0
	global_store_short v[6:7], v3, off

; DI unsigned pk2(float lo, float hi) { f32x2 v = {lo, hi}; bf16x2_t b = __builtin_convertvector(v, bf16x2_t); return __builtin_bit_cast(unsigned, b); }
; DI float fexp2(float x) { return __builtin_amdgcn_exp2f(x); }
; DI float frcp(float x) { return __builtin_amdgcn_rcpf(x); }
; DI int crow(int i, int h) { return (i & 3) + 8 * (i >> 2) + 4 * h; }
; DI void sample_gemm(ArgsP AP0, LAS unsigned char* lds, const pg8::Gemm g, int mode, int l) {
;     ...
;             for (int i = 0; i < 16; ++i) {
;                 float v = acc[i];
; #pragma unroll
;                 for (int w = 0; w < 7; ++w) v += red[(w * 16 + i) * 64 + lane];
;                 const int rr = 32 * wm + crow(i, h), row = RP + rr, bs = rr >> 4, s = rr & 15;
;                 if (mode == 1) { const float t = 0.7978845608028654f * (v + 0.044715f * v * v * v); v = v * frcp(1.f + fexp2(-2.f * LOG2E * t)); }
;                 else if (mode == 2 || mode == 3) {
;                     const int region = col >> 10;
;                     if (mode == 2 && region < 2 && (n0 & 32) == 0) {
;                         const float pv = __shfl_xor(v, 8);
;                         if (r32 < 16) { const f32x2 cs = *(const f32x2*)((const float*)(ws + WS_ROPE) + (size_t)(2048 + s) * 16 + 2 * (r32 & 7)); v = v * cs[0] + ((r32 < 8) ? -pv : pv) * cs[1]; }
;                     }
;                     if (region == 0) v *= (mode == 2) ? QSCALE_DIFF : QSCALE_SB;
;                     else { const int kc = col & 1023;
;                         float* dst = outp + (region == 1 ? (mode == 2 ? O_DKS : O_SKS) : (mode == 2 ? O_DVS : O_SVS)) + (size_t)rr * DM + kc; *dst = v;
;                         bf16* cd = (bf16*)(ws + WS_BIG + 4 * U1 + (region == 1 ? 0 : CACHE_B)) + ((size_t)bs * CROWS + 2048 + s) * DM + kc; *cd = (bf16)(pk2(v, 0.f) & 0xffffu); }
;                 } else if (mode == 4) {
;                     const int tl = col >> 8, j = col & 255, chn = tl * 128 + (j & 127); const bool isg = j < 128;
;                     if (isg && s >= SSEQ - 2) outp[O_FS + (size_t)l * NBS * 2 * DFF + ((size_t)bs * 2 + (s - (SSEQ - 2))) * DFF + chn] = v;
;                     ((bf16*)(ws + WS_SGU))[(size_t)rr * 5632 + (isg ? chn : DFF + chn)] = (bf16)(pk2(v, 0.f) & 0xffffu);
.LBB0_549:
	ds_read2st64_b32 v[2:3], v150 offset0:14 offset1:30
	ds_read2st64_b32 v[236:237], v150 offset0:46 offset1:62
	ds_read2st64_b32 v[238:239], v150 offset0:78 offset1:94
	ds_read_b32 v240, v150 offset:28160
	s_mov_b64 s[2:3], -1
	s_and_b64 vcc, exec, s[58:59]
	s_waitcnt lgkmcnt(3)
	v_add_f32_e32 v2, v14, v2
	v_add_f32_e32 v4, v2, v3
	s_waitcnt lgkmcnt(2)
	v_add_f32_e32 v2, v4, v236
	v_add_f32_e32 v4, v2, v237
	s_waitcnt lgkmcnt(1)
	v_add_f32_e32 v2, v4, v238
	v_add_f32_e32 v2, v2, v239
	v_or_b32_e32 v4, s84, v187
	s_waitcnt lgkmcnt(0)
	v_add_f32_e32 v2, v2, v240
	s_cbranch_vccnz .LBB0_608
	v_lshrrev_b32_e32 v5, 4, v4
	s_and_b64 vcc, exec, s[56:57]
	s_cbranch_vccnz .LBB0_556
	s_andn2_b64 vcc, exec, s[16:17]
	s_cbranch_vccnz .LBB0_555
	s_and_b64 s[6:7], s[52:53], s[48:49]
	s_and_saveexec_b64 s[2:3], s[6:7]
	s_cbranch_execz .LBB0_554
	v_lshlrev_b32_e32 v3, 1, v5
	s_movk_i32 s6, 0x2c00
	v_mad_u64_u32 v[6:7], s[6:7], v3, s6, v[0:1]
	global_store_dword v[6:7], v2, off

; template <class Epi, class Sched, bool ALIGN_EPI = false, bool SP2 = false>
; __device__ __forceinline__ void gemm_phase(PG8_LAS unsigned char* lds, const Gemm g, const Sched& S, const Epi& E) {
;     ...
; #pragma unroll
;         for (int a = 0; a < 2; ++a)
; #pragma unroll
;             for (int b = 0; b < 2; ++b)
; #pragma unroll
;                 for (int m = 0; m < 4; ++m)
; #pragma unroll
;                     for (int n = 0; n < 2; ++n) acc[a][b][m][n] = (f32x4){0.f, 0.f, 0.f, 0.f};
;         cur = nxt; cA = nA; cB = nB; ++ui;
.LBB0_660:
	s_add_u32 s0, s14, 0x80
	s_addc_u32 s1, s15, 0
	s_add_u32 s9, s2, 0x100
	v_mov_b32_e32 v4, 0
	s_addc_u32 s14, s3, 0
	s_mov_b32 s2, 0
	v_mov_b32_e32 v5, v4
	v_mov_b32_e32 v6, v4
	v_mov_b32_e32 v7, v4
	v_mov_b32_e32 v68, v4
	v_mov_b32_e32 v69, v4
	v_mov_b32_e32 v70, v4
	v_mov_b32_e32 v71, v4
	v_mov_b32_e32 v8, v4
	v_mov_b32_e32 v9, v4
	v_mov_b32_e32 v10, v4
	v_mov_b32_e32 v11, v4
	v_mov_b32_e32 v72, v4
	v_mov_b32_e32 v73, v4
	v_mov_b32_e32 v74, v4
	v_mov_b32_e32 v75, v4
	v_mov_b32_e32 v16, v4
	v_mov_b32_e32 v17, v4
	v_mov_b32_e32 v18, v4
	v_mov_b32_e32 v19, v4
	v_mov_b32_e32 v80, v4
	v_mov_b32_e32 v81, v4
	v_mov_b32_e32 v82, v4
	v_mov_b32_e32 v83, v4
	v_mov_b32_e32 v28, v4
	v_mov_b32_e32 v29, v4
	v_mov_b32_e32 v30, v4
	v_mov_b32_e32 v31, v4
	v_mov_b32_e32 v92, v4
	v_mov_b32_e32 v93, v4
	v_mov_b32_e32 v94, v4
	v_mov_b32_e32 v95, v4
	v_mov_b32_e32 v0, v4
	v_mov_b32_e32 v1, v4
	v_mov_b32_e32 v2, v4
	v_mov_b32_e32 v3, v4
	v_mov_b32_e32 v64, v4
	v_mov_b32_e32 v65, v4
	v_mov_b32_e32 v66, v4
	v_mov_b32_e32 v67, v4
	v_mov_b32_e32 v12, v4
	v_mov_b32_e32 v13, v4
	v_mov_b32_e32 v14, v4
	v_mov_b32_e32 v15, v4
	v_mov_b32_e32 v76, v4
	v_mov_b32_e32 v77, v4
	v_mov_b32_e32 v78, v4
	v_mov_b32_e32 v79, v4
	v_mov_b32_e32 v20, v4
	v_mov_b32_e32 v21, v4
	v_mov_b32_e32 v22, v4
	v_mov_b32_e32 v23, v4
	v_mov_b32_e32 v84, v4
	v_mov_b32_e32 v85, v4
	v_mov_b32_e32 v86, v4
	v_mov_b32_e32 v87, v4
	v_mov_b32_e32 v24, v4
	v_mov_b32_e32 v25, v4
	v_mov_b32_e32 v26, v4
	v_mov_b32_e32 v27, v4
	v_mov_b32_e32 v88, v4
	v_mov_b32_e32 v89, v4
	v_mov_b32_e32 v90, v4
	v_mov_b32_e32 v91, v4
	v_mov_b32_e32 v36, v4
	v_mov_b32_e32 v37, v4
	v_mov_b32_e32 v38, v4
	v_mov_b32_e32 v39, v4
	v_mov_b32_e32 v102, v4
	v_mov_b32_e32 v103, v4
	v_mov_b32_e32 v104, v4
	v_mov_b32_e32 v105, v4
	v_mov_b32_e32 v40, v4
	v_mov_b32_e32 v41, v4
	v_mov_b32_e32 v42, v4
	v_mov_b32_e32 v43, v4
	v_mov_b32_e32 v106, v4
	v_mov_b32_e32 v107, v4
	v_mov_b32_e32 v108, v4
	v_mov_b32_e32 v109, v4
	v_mov_b32_e32 v48, v4
	v_mov_b32_e32 v49, v4
	v_mov_b32_e32 v50, v4
	v_mov_b32_e32 v51, v4
	v_mov_b32_e32 v114, v4
	v_mov_b32_e32 v115, v4
	v_mov_b32_e32 v116, v4
	v_mov_b32_e32 v117, v4
	v_mov_b32_e32 v60, v4
	v_mov_b32_e32 v61, v4
	v_mov_b32_e32 v62, v4
	v_mov_b32_e32 v63, v4
	v_mov_b32_e32 v126, v4
	v_mov_b32_e32 v127, v4
	v_mov_b32_e32 v128, v4
	v_mov_b32_e32 v129, v4
	v_mov_b32_e32 v32, v4
	v_mov_b32_e32 v33, v4
	v_mov_b32_e32 v34, v4
	v_mov_b32_e32 v35, v4
	v_mov_b32_e32 v98, v4
	v_mov_b32_e32 v99, v4
	v_mov_b32_e32 v100, v4
	v_mov_b32_e32 v101, v4
	v_mov_b32_e32 v44, v4
	v_mov_b32_e32 v45, v4
	v_mov_b32_e32 v46, v4
	v_mov_b32_e32 v47, v4
	v_mov_b32_e32 v110, v4
	v_mov_b32_e32 v111, v4
	v_mov_b32_e32 v112, v4
	v_mov_b32_e32 v113, v4
	v_mov_b32_e32 v52, v4
	v_mov_b32_e32 v53, v4
	v_mov_b32_e32 v54, v4
	v_mov_b32_e32 v55, v4
	v_mov_b32_e32 v118, v4
	v_mov_b32_e32 v119, v4
	v_mov_b32_e32 v120, v4
	v_mov_b32_e32 v121, v4
	v_mov_b32_e32 v56, v4
	v_mov_b32_e32 v57, v4
	v_mov_b32_e32 v58, v4
	v_mov_b32_e32 v59, v4
	v_mov_b32_e32 v122, v4
	v_mov_b32_e32 v123, v4
	v_mov_b32_e32 v124, v4
	v_mov_b32_e32 v125, v4
	v_add_u32_e32 v234, s60, v150
	v_add_u32_e32 v235, s60, v154
.LBB0_661:
	s_add_i32 s15, s2, 2
	s_add_u32 s6, s0, 0x80
	s_mov_b32 s7, 0x10000
	s_addc_u32 s3, s1, 0
	s_addk_i32 s7, 0x100
	s_waitcnt lgkmcnt(0)
	v_add_u32_e32 v96, s7, v157
	ds_read_b128 v[130:133], v96
	ds_read_b128 v[134:137], v96 offset:1024
	ds_read_b128 v[138:141], v96 offset:2048
	ds_read_b128 v[142:145], v96 offset:3072
	v_add_u32_e32 v96, s77, v157
	ds_read_b128 v[172:175], v96
	ds_read_b128 v[176:179], v96 offset:1024
	ds_read_b128 v[180:183], v96 offset:2048
	ds_read_b128 v[184:187], v96 offset:3072
	s_cmp_eq_u32 s41, s2
	s_cselect_b32 s2, s24, s6
	s_cselect_b32 s3, s25, s3
	s_cselect_b32 s17, s27, s14
	s_cselect_b32 s16, s26, s9
	s_add_i32 m0, s72, 0xc000
	ds_read_b128 v[188:191], v193
	ds_read_b128 v[194:197], v193 offset:1024
	ds_read_b128 v[198:201], v193 offset:2048
	ds_read_b128 v[202:205], v193 offset:3072
	ds_read_b128 v[206:209], v193 offset:4096
	ds_read_b128 v[210:213], v193 offset:5120
	ds_read_b128 v[214:217], v193 offset:6144
	ds_read_b128 v[228:231], v193 offset:7168
	global_load_lds_dwordx4 v168, s[0:1]
	s_add_i32 m0, s72, 0xe000
	s_nop 0
	global_load_lds_dwordx4 v170, s[0:1]
	s_waitcnt vmcnt(8)
	s_waitcnt lgkmcnt(0)
	s_barrier
	s_setprio 1
	s_waitcnt lgkmcnt(0)
	v_mfma_f32_16x16x32_bf16 v[122:125], v[130:133], v[188:191], v[122:125]
	v_mfma_f32_16x16x32_bf16 v[56:59], v[138:141], v[188:191], v[56:59]
	v_mfma_f32_16x16x32_bf16 v[118:121], v[130:133], v[198:201], v[118:121]
	v_mfma_f32_16x16x32_bf16 v[52:55], v[138:141], v[198:201], v[52:55]
	v_mfma_f32_16x16x32_bf16 v[110:113], v[130:133], v[206:209], v[110:113]
	v_mfma_f32_16x16x32_bf16 v[44:47], v[138:141], v[206:209], v[44:47]
	v_mfma_f32_16x16x32_bf16 v[98:101], v[130:133], v[214:217], v[98:101]
	v_mfma_f32_16x16x32_bf16 v[32:35], v[138:141], v[214:217], v[32:35]
	v_mfma_f32_16x16x32_bf16 v[122:125], v[134:137], v[194:197], v[122:125]
	v_mfma_f32_16x16x32_bf16 v[56:59], v[142:145], v[194:197], v[56:59]
	v_mfma_f32_16x16x32_bf16 v[118:121], v[134:137], v[202:205], v[118:121]
	v_mfma_f32_16x16x32_bf16 v[52:55], v[142:145], v[202:205], v[52:55]
	v_mfma_f32_16x16x32_bf16 v[110:113], v[134:137], v[210:213], v[110:113]
	v_mfma_f32_16x16x32_bf16 v[44:47], v[142:145], v[210:213], v[44:47]
	v_mfma_f32_16x16x32_bf16 v[98:101], v[134:137], v[228:231], v[98:101]
	v_mfma_f32_16x16x32_bf16 v[32:35], v[142:145], v[228:231], v[32:35]
	s_setprio 0
	s_setprio 1
	v_mfma_f32_16x16x32_bf16 v[126:129], v[172:175], v[188:191], v[126:129]
	v_mfma_f32_16x16x32_bf16 v[60:63], v[180:183], v[188:191], v[60:63]
	v_mfma_f32_16x16x32_bf16 v[114:117], v[172:175], v[198:201], v[114:117]
	v_mfma_f32_16x16x32_bf16 v[48:51], v[180:183], v[198:201], v[48:51]
	v_mfma_f32_16x16x32_bf16 v[106:109], v[172:175], v[206:209], v[106:109]
	v_mfma_f32_16x16x32_bf16 v[40:43], v[180:183], v[206:209], v[40:43]
	v_mfma_f32_16x16x32_bf16 v[102:105], v[172:175], v[214:217], v[102:105]
	v_mfma_f32_16x16x32_bf16 v[36:39], v[180:183], v[214:217], v[36:39]
	v_mfma_f32_16x16x32_bf16 v[126:129], v[176:179], v[194:197], v[126:129]
	v_mfma_f32_16x16x32_bf16 v[60:63], v[184:187], v[194:197], v[60:63]
	v_mfma_f32_16x16x32_bf16 v[114:117], v[176:179], v[202:205], v[114:117]
	v_mfma_f32_16x16x32_bf16 v[48:51], v[184:187], v[202:205], v[48:51]
	v_mfma_f32_16x16x32_bf16 v[106:109], v[176:179], v[210:213], v[106:109]
	v_mfma_f32_16x16x32_bf16 v[40:43], v[184:187], v[210:213], v[40:43]
	v_mfma_f32_16x16x32_bf16 v[102:105], v[176:179], v[228:231], v[102:105]
	v_mfma_f32_16x16x32_bf16 v[36:39], v[184:187], v[228:231], v[36:39]
	s_setprio 0
	s_barrier
; #define PG8_STAGE(bufoff, gbase, voff) do { _Pragma("unroll") for (int _i = 0; _i < 2; ++_i) \
;         __builtin_amdgcn_global_load_lds((const unsigned*)((const char*)(gbase) + (voff)[_i]), (PG8_LAS unsigned*)(lds + (bufoff) + ldsw + _i * 8192), 16, 0, 0); } while (0)
; #define PG8_LDA(dst, b, h) do { _Pragma("unroll") for (int m = 0; m < 4; ++m) _Pragma("unroll") for (int k = 0; k < 2; ++k) dst[m][k] = *(const PG8_LAS bf16x8*)(lds + PG8_SA(b, h) + aoff + m * 2048 + k * 1024); } while (0)
; #define PG8_LDB(dst, b, h) do { _Pragma("unroll") for (int n = 0; n < 2; ++n) _Pragma("unroll") for (int k = 0; k < 2; ++k) dst[n][k] = *(const PG8_LAS bf16x8*)(lds + PG8_SB(b, h) + boff + n * 2048 + k * 1024); } while (0)
; #define PG8_MMA(ai, bj, At, Bt) do { __builtin_amdgcn_s_setprio(1); _Pragma("unroll") for (int m = 0; m < 4; ++m) _Pragma("unroll") for (int n = 0; n < 2; ++n) _Pragma("unroll") for (int k = 0; k < 2; ++k) \
;         acc[ai][bj][m][n] = __builtin_amdgcn_mfma_f32_16x16x32_bf16(Bt[n][k], At[m][k], acc[ai][bj][m][n], 0, 0, 0); __builtin_amdgcn_s_setprio(0); } while (0)
; #define PG8_WAIT_V(n) asm volatile("s_waitcnt vmcnt(" #n ")" ::: "memory")
; #define PG8_WAIT_L(n) asm volatile("s_waitcnt lgkmcnt(" #n ")" ::: "memory")
; #define PG8_BAR __builtin_amdgcn_s_barrier()
; #define PG8_SCHED __builtin_amdgcn_sched_barrier(0)
; template <class Epi, class Sched, bool ALIGN_EPI = false, bool SP2 = false>
; __device__ __forceinline__ void gemm_phase(PG8_LAS unsigned char* lds, const Gemm g, const Sched& S, const Epi& E) {
;     ...
;             PG8_LDA(At, 0, 1); PG8_STAGE(PG8_SB(0, 0), b2, voffB); PG8_STAGE(PG8_SB(0, 1), b2 + hstepB, voffB); PG8_STAGE(PG8_SA(0, 0), a2, voffA);
;             PG8_WAIT_V(8); PG8_WAIT_L(0); PG8_BAR; PG8_MMA(1, 0, At, B0); PG8_MMA(1, 1, At, B1); PG8_BAR; PG8_SCHED;
;             PG8_LDB(B0, 1, 0); PG8_LDB(B1, 1, 1); PG8_SCHED; PG8_LDA(At, 1, 0); PG8_STAGE(PG8_SA(0, 1), a2 + hstepA, voffA);
;             PG8_WAIT_V(8); PG8_WAIT_L(0); PG8_BAR; PG8_MMA(0, 0, At, B0); PG8_MMA(0, 1, At, B1); PG8_BAR; PG8_SCHED;
	s_add_i32 s6, s7, s71
	s_mov_b32 m0, s6
	ds_read_b128 v[188:191], v193 offset:16384
	ds_read_b128 v[194:197], v193 offset:17408
	ds_read_b128 v[198:201], v193 offset:18432
	ds_read_b128 v[202:205], v193 offset:19456
	ds_read_b128 v[206:209], v193 offset:20480
	ds_read_b128 v[210:213], v193 offset:21504
	ds_read_b128 v[214:217], v193 offset:22528
	ds_read_b128 v[228:231], v193 offset:23552
	global_load_lds_dwordx4 v150, s[16:17]
	s_add_i32 m0, s6, 0x2000
	s_add_i32 s6, s77, s71
	global_load_lds_dwordx4 v154, s[16:17]
	s_mov_b32 m0, s6
	s_nop 0
	global_load_lds_dwordx4 v234, s[16:17]
	s_add_i32 m0, s6, 0x2000
	s_nop 0
	global_load_lds_dwordx4 v235, s[16:17]
	s_mov_b32 m0, s72
	s_nop 0
	global_load_lds_dwordx4 v148, s[2:3]
	s_mov_b32 m0, s73
	s_nop 0
	global_load_lds_dwordx4 v152, s[2:3]
	s_waitcnt vmcnt(8)
	s_waitcnt lgkmcnt(0)
	s_barrier
	s_setprio 1
	s_waitcnt lgkmcnt(0)
	v_mfma_f32_16x16x32_bf16 v[88:91], v[130:133], v[188:191], v[88:91]
	v_mfma_f32_16x16x32_bf16 v[24:27], v[138:141], v[188:191], v[24:27]
	v_mfma_f32_16x16x32_bf16 v[84:87], v[130:133], v[198:201], v[84:87]
	v_mfma_f32_16x16x32_bf16 v[20:23], v[138:141], v[198:201], v[20:23]
	v_mfma_f32_16x16x32_bf16 v[76:79], v[130:133], v[206:209], v[76:79]
	v_mfma_f32_16x16x32_bf16 v[12:15], v[138:141], v[206:209], v[12:15]
	v_mfma_f32_16x16x32_bf16 v[64:67], v[130:133], v[214:217], v[64:67]
	v_mfma_f32_16x16x32_bf16 v[0:3], v[138:141], v[214:217], v[0:3]
	v_mfma_f32_16x16x32_bf16 v[88:91], v[134:137], v[194:197], v[88:91]
	v_mfma_f32_16x16x32_bf16 v[24:27], v[142:145], v[194:197], v[24:27]
	v_mfma_f32_16x16x32_bf16 v[84:87], v[134:137], v[202:205], v[84:87]
	v_mfma_f32_16x16x32_bf16 v[20:23], v[142:145], v[202:205], v[20:23]
	v_mfma_f32_16x16x32_bf16 v[76:79], v[134:137], v[210:213], v[76:79]
	v_mfma_f32_16x16x32_bf16 v[12:15], v[142:145], v[210:213], v[12:15]
	v_mfma_f32_16x16x32_bf16 v[64:67], v[134:137], v[228:231], v[64:67]
	v_mfma_f32_16x16x32_bf16 v[0:3], v[142:145], v[228:231], v[0:3]
	s_setprio 0
	s_setprio 1
	v_mfma_f32_16x16x32_bf16 v[92:95], v[172:175], v[188:191], v[92:95]
	v_mfma_f32_16x16x32_bf16 v[28:31], v[180:183], v[188:191], v[28:31]
	v_mfma_f32_16x16x32_bf16 v[80:83], v[172:175], v[198:201], v[80:83]
	v_mfma_f32_16x16x32_bf16 v[16:19], v[180:183], v[198:201], v[16:19]
	v_mfma_f32_16x16x32_bf16 v[72:75], v[172:175], v[206:209], v[72:75]
	v_mfma_f32_16x16x32_bf16 v[8:11], v[180:183], v[206:209], v[8:11]
	v_mfma_f32_16x16x32_bf16 v[68:71], v[172:175], v[214:217], v[68:71]
	v_mfma_f32_16x16x32_bf16 v[4:7], v[180:183], v[214:217], v[4:7]
	v_mfma_f32_16x16x32_bf16 v[92:95], v[176:179], v[194:197], v[92:95]
	v_mfma_f32_16x16x32_bf16 v[28:31], v[184:187], v[194:197], v[28:31]
	v_mfma_f32_16x16x32_bf16 v[80:83], v[176:179], v[202:205], v[80:83]
	v_mfma_f32_16x16x32_bf16 v[16:19], v[184:187], v[202:205], v[16:19]
	v_mfma_f32_16x16x32_bf16 v[72:75], v[176:179], v[210:213], v[72:75]
	v_mfma_f32_16x16x32_bf16 v[8:11], v[184:187], v[210:213], v[8:11]
	v_mfma_f32_16x16x32_bf16 v[68:71], v[176:179], v[228:231], v[68:71]
	v_mfma_f32_16x16x32_bf16 v[4:7], v[184:187], v[228:231], v[4:7]
	s_setprio 0
	s_barrier
	v_add_u32_e32 v96, s33, v157
	ds_read_b128 v[130:133], v96
	ds_read_b128 v[134:137], v96 offset:1024
	ds_read_b128 v[138:141], v96 offset:2048
	ds_read_b128 v[142:145], v96 offset:3072
	v_add_u32_e32 v96, s12, v157
	ds_read_b128 v[172:175], v96
	ds_read_b128 v[176:179], v96 offset:1024
	ds_read_b128 v[180:183], v96 offset:2048
	ds_read_b128 v[184:187], v96 offset:3072
	s_mov_b32 m0, s62
	ds_read_b128 v[188:191], v193 offset:32768
	ds_read_b128 v[194:197], v193 offset:33792
	ds_read_b128 v[198:201], v193 offset:34816
	ds_read_b128 v[202:205], v193 offset:35840
	ds_read_b128 v[206:209], v193 offset:36864
	ds_read_b128 v[210:213], v193 offset:37888
	ds_read_b128 v[214:217], v193 offset:38912
	ds_read_b128 v[228:231], v193 offset:39936
	global_load_lds_dwordx4 v168, s[2:3]
	s_mov_b32 m0, s63
	s_nop 0
	global_load_lds_dwordx4 v170, s[2:3]
	s_waitcnt vmcnt(8)
	s_waitcnt lgkmcnt(0)
	s_barrier
; #define PG8_STAGE(bufoff, gbase, voff) do { _Pragma("unroll") for (int _i = 0; _i < 2; ++_i) \
;         __builtin_amdgcn_global_load_lds((const unsigned*)((const char*)(gbase) + (voff)[_i]), (PG8_LAS unsigned*)(lds + (bufoff) + ldsw + _i * 8192), 16, 0, 0); } while (0)
; #define PG8_LDA(dst, b, h) do { _Pragma("unroll") for (int m = 0; m < 4; ++m) _Pragma("unroll") for (int k = 0; k < 2; ++k) dst[m][k] = *(const PG8_LAS bf16x8*)(lds + PG8_SA(b, h) + aoff + m * 2048 + k * 1024); } while (0)
; #define PG8_MMA(ai, bj, At, Bt) do { __builtin_amdgcn_s_setprio(1); _Pragma("unroll") for (int m = 0; m < 4; ++m) _Pragma("unroll") for (int n = 0; n < 2; ++n) _Pragma("unroll") for (int k = 0; k < 2; ++k) \
;         acc[ai][bj][m][n] = __builtin_amdgcn_mfma_f32_16x16x32_bf16(Bt[n][k], At[m][k], acc[ai][bj][m][n], 0, 0, 0); __builtin_amdgcn_s_setprio(0); } while (0)
; #define PG8_WAIT_V(n) asm volatile("s_waitcnt vmcnt(" #n ")" ::: "memory")
; #define PG8_WAIT_L(n) asm volatile("s_waitcnt lgkmcnt(" #n ")" ::: "memory")
; #define PG8_BAR __builtin_amdgcn_s_barrier()
; #define PG8_SCHED __builtin_amdgcn_sched_barrier(0)
; template <class Epi, class Sched, bool ALIGN_EPI = false, bool SP2 = false>
; __device__ __forceinline__ void gemm_phase(PG8_LAS unsigned char* lds, const Gemm g, const Sched& S, const Epi& E) {
;     ...
;         for (int t = 0; t < nt; t += 2) {
;     ...
;             PG8_WAIT_V(8); PG8_WAIT_L(0); PG8_BAR; PG8_MMA(0, 0, At, B0); PG8_MMA(0, 1, At, B1); PG8_BAR; PG8_SCHED;
;             PG8_LDA(At, 1, 1); PG8_STAGE(PG8_SB(1, 0), b3, voffB); PG8_STAGE(PG8_SB(1, 1), b3 + hstepB, voffB); PG8_STAGE(PG8_SA(1, 0), a3, voffA);
;             PG8_WAIT_V(8); PG8_WAIT_L(0); PG8_BAR; PG8_MMA(1, 0, At, B0); PG8_MMA(1, 1, At, B1); PG8_BAR; PG8_SCHED;
	s_setprio 1
	s_waitcnt lgkmcnt(0)
	v_mfma_f32_16x16x32_bf16 v[122:125], v[130:133], v[188:191], v[122:125]
	v_mfma_f32_16x16x32_bf16 v[56:59], v[138:141], v[188:191], v[56:59]
	v_mfma_f32_16x16x32_bf16 v[118:121], v[130:133], v[198:201], v[118:121]
	v_mfma_f32_16x16x32_bf16 v[52:55], v[138:141], v[198:201], v[52:55]
	v_mfma_f32_16x16x32_bf16 v[110:113], v[130:133], v[206:209], v[110:113]
	v_mfma_f32_16x16x32_bf16 v[44:47], v[138:141], v[206:209], v[44:47]
	v_mfma_f32_16x16x32_bf16 v[98:101], v[130:133], v[214:217], v[98:101]
	v_mfma_f32_16x16x32_bf16 v[32:35], v[138:141], v[214:217], v[32:35]
	v_mfma_f32_16x16x32_bf16 v[122:125], v[134:137], v[194:197], v[122:125]
	v_mfma_f32_16x16x32_bf16 v[56:59], v[142:145], v[194:197], v[56:59]
	v_mfma_f32_16x16x32_bf16 v[118:121], v[134:137], v[202:205], v[118:121]
	v_mfma_f32_16x16x32_bf16 v[52:55], v[142:145], v[202:205], v[52:55]
	v_mfma_f32_16x16x32_bf16 v[110:113], v[134:137], v[210:213], v[110:113]
	v_mfma_f32_16x16x32_bf16 v[44:47], v[142:145], v[210:213], v[44:47]
	v_mfma_f32_16x16x32_bf16 v[98:101], v[134:137], v[228:231], v[98:101]
	v_mfma_f32_16x16x32_bf16 v[32:35], v[142:145], v[228:231], v[32:35]
	s_setprio 0
	s_setprio 1
	v_mfma_f32_16x16x32_bf16 v[126:129], v[172:175], v[188:191], v[126:129]
	v_mfma_f32_16x16x32_bf16 v[60:63], v[180:183], v[188:191], v[60:63]
	v_mfma_f32_16x16x32_bf16 v[114:117], v[172:175], v[198:201], v[114:117]
	v_mfma_f32_16x16x32_bf16 v[48:51], v[180:183], v[198:201], v[48:51]
	v_mfma_f32_16x16x32_bf16 v[106:109], v[172:175], v[206:209], v[106:109]
	v_mfma_f32_16x16x32_bf16 v[40:43], v[180:183], v[206:209], v[40:43]
	v_mfma_f32_16x16x32_bf16 v[102:105], v[172:175], v[214:217], v[102:105]
	v_mfma_f32_16x16x32_bf16 v[36:39], v[180:183], v[214:217], v[36:39]
	v_mfma_f32_16x16x32_bf16 v[126:129], v[176:179], v[194:197], v[126:129]
	v_mfma_f32_16x16x32_bf16 v[60:63], v[184:187], v[194:197], v[60:63]
	v_mfma_f32_16x16x32_bf16 v[114:117], v[176:179], v[202:205], v[114:117]
	v_mfma_f32_16x16x32_bf16 v[48:51], v[184:187], v[202:205], v[48:51]
	v_mfma_f32_16x16x32_bf16 v[106:109], v[176:179], v[210:213], v[106:109]
	v_mfma_f32_16x16x32_bf16 v[40:43], v[184:187], v[210:213], v[40:43]
	v_mfma_f32_16x16x32_bf16 v[102:105], v[176:179], v[228:231], v[102:105]
	v_mfma_f32_16x16x32_bf16 v[36:39], v[184:187], v[228:231], v[36:39]
	s_setprio 0
	s_barrier
	s_add_i32 s6, s33, s71
	s_mov_b32 m0, s6
	s_add_u32 s16, s16, 0x80
	s_addc_u32 s17, s17, 0
	s_add_u32 s2, s2, 0x80
	s_addc_u32 s3, s3, 0
	ds_read_b128 v[188:191], v193 offset:49152
	ds_read_b128 v[194:197], v193 offset:50176
	ds_read_b128 v[198:201], v193 offset:51200
	ds_read_b128 v[202:205], v193 offset:52224
	ds_read_b128 v[206:209], v193 offset:53248
	ds_read_b128 v[210:213], v193 offset:54272
	ds_read_b128 v[214:217], v193 offset:55296
	ds_read_b128 v[228:231], v193 offset:56320
	global_load_lds_dwordx4 v150, s[16:17]
	s_add_i32 m0, s6, 0x2000
	s_add_i32 s6, s12, s71
	global_load_lds_dwordx4 v154, s[16:17]
	s_mov_b32 m0, s6
	s_nop 0
	global_load_lds_dwordx4 v234, s[16:17]
	s_add_i32 m0, s6, 0x2000
	s_nop 0
	global_load_lds_dwordx4 v235, s[16:17]
	s_mov_b32 m0, s20
	s_nop 0
	global_load_lds_dwordx4 v148, s[2:3]
	s_mov_b32 m0, s21
	s_nop 0
	global_load_lds_dwordx4 v152, s[2:3]
	s_waitcnt vmcnt(8)
	s_waitcnt lgkmcnt(0)
	s_barrier
	s_setprio 1
	s_waitcnt lgkmcnt(0)
	v_mfma_f32_16x16x32_bf16 v[88:91], v[130:133], v[188:191], v[88:91]
	v_mfma_f32_16x16x32_bf16 v[24:27], v[138:141], v[188:191], v[24:27]
	v_mfma_f32_16x16x32_bf16 v[84:87], v[130:133], v[198:201], v[84:87]
	v_mfma_f32_16x16x32_bf16 v[20:23], v[138:141], v[198:201], v[20:23]
	v_mfma_f32_16x16x32_bf16 v[76:79], v[130:133], v[206:209], v[76:79]
	v_mfma_f32_16x16x32_bf16 v[12:15], v[138:141], v[206:209], v[12:15]
	v_mfma_f32_16x16x32_bf16 v[64:67], v[130:133], v[214:217], v[64:67]
	v_mfma_f32_16x16x32_bf16 v[0:3], v[138:141], v[214:217], v[0:3]
	v_mfma_f32_16x16x32_bf16 v[88:91], v[134:137], v[194:197], v[88:91]
	v_mfma_f32_16x16x32_bf16 v[24:27], v[142:145], v[194:197], v[24:27]
	v_mfma_f32_16x16x32_bf16 v[84:87], v[134:137], v[202:205], v[84:87]
	v_mfma_f32_16x16x32_bf16 v[20:23], v[142:145], v[202:205], v[20:23]
	v_mfma_f32_16x16x32_bf16 v[76:79], v[134:137], v[210:213], v[76:79]
	v_mfma_f32_16x16x32_bf16 v[12:15], v[142:145], v[210:213], v[12:15]
	v_mfma_f32_16x16x32_bf16 v[64:67], v[134:137], v[228:231], v[64:67]
	v_mfma_f32_16x16x32_bf16 v[0:3], v[142:145], v[228:231], v[0:3]
	s_setprio 0
	s_setprio 1
	v_mfma_f32_16x16x32_bf16 v[92:95], v[172:175], v[188:191], v[92:95]
	v_mfma_f32_16x16x32_bf16 v[28:31], v[180:183], v[188:191], v[28:31]
	v_mfma_f32_16x16x32_bf16 v[80:83], v[172:175], v[198:201], v[80:83]
	v_mfma_f32_16x16x32_bf16 v[16:19], v[180:183], v[198:201], v[16:19]
	v_mfma_f32_16x16x32_bf16 v[72:75], v[172:175], v[206:209], v[72:75]
	v_mfma_f32_16x16x32_bf16 v[8:11], v[180:183], v[206:209], v[8:11]
	v_mfma_f32_16x16x32_bf16 v[68:71], v[172:175], v[214:217], v[68:71]
	v_mfma_f32_16x16x32_bf16 v[4:7], v[180:183], v[214:217], v[4:7]
	v_mfma_f32_16x16x32_bf16 v[92:95], v[176:179], v[194:197], v[92:95]
	v_mfma_f32_16x16x32_bf16 v[28:31], v[184:187], v[194:197], v[28:31]
	v_mfma_f32_16x16x32_bf16 v[80:83], v[176:179], v[202:205], v[80:83]
	v_mfma_f32_16x16x32_bf16 v[16:19], v[184:187], v[202:205], v[16:19]
	v_mfma_f32_16x16x32_bf16 v[72:75], v[176:179], v[210:213], v[72:75]
	v_mfma_f32_16x16x32_bf16 v[8:11], v[184:187], v[210:213], v[8:11]
	v_mfma_f32_16x16x32_bf16 v[68:71], v[176:179], v[228:231], v[68:71]
	v_mfma_f32_16x16x32_bf16 v[4:7], v[184:187], v[228:231], v[4:7]
	s_setprio 0
	s_barrier
	s_add_u32 s0, s0, 0x100
	s_addc_u32 s1, s1, 0
	s_add_u32 s9, s9, 0x100
	s_addc_u32 s14, s14, 0
	s_cmp_ge_u32 s15, s40
	s_mov_b32 s2, s15
	s_cbranch_scc0 .LBB0_661
	s_and_b64 vcc, exec, s[78:79]
	s_cbranch_vccz .LBB0_664
	s_barrier

; #define NORM_LDX(rowoff) do { if (n == 0) xn[j] = *(const f32x4*)(xsrc + (size_t)(rowoff) * DM + lane * 4 + 256 * j); \
;             else xr[j] = __builtin_nontemporal_load((const u32x2*)(X + (size_t)(r0 + (rowoff)) * DM + lane * 4 + 256 * j)); } while (0)
; DI void phase_norm(ArgsP AP, int n, bool dry) {
;     ...
;             if (i + 1 < nrows) {
; #pragma unroll
;                 for (int j = 0; j < 4; ++j) { NORM_LDX(i + 1); if (has_prev) mn[j] = __builtin_nontemporal_load((const u32x2*)(H + (size_t)(r + 1) * DM + lane * 4 + 256 * j)); }
;             }
.LBB0_1135:
	global_load_dwordx4 v[64:67], v[114:115], off
	v_mov_b32_e32 v100, v124
	v_mov_b32_e32 v101, v125
	v_lshl_add_u64 v[134:135], v[84:85], 0, v[68:69]
	s_and_b64 vcc, exec, s[42:43]
	v_mov_b64_e32 v[116:117], v[112:113]
	s_cbranch_vccz .LBB0_1113
	s_branch .LBB0_1114

; #define NORM_LDX(rowoff) do { if (n == 0) xn[j] = *(const f32x4*)(xsrc + (size_t)(rowoff) * DM + lane * 4 + 256 * j); \
;             else xr[j] = __builtin_nontemporal_load((const u32x2*)(X + (size_t)(r0 + (rowoff)) * DM + lane * 4 + 256 * j)); } while (0)
; DI void phase_norm(ArgsP AP, int n, bool dry) {
;     ...
;             if (i + 1 < nrows) {
; #pragma unroll
;                 for (int j = 0; j < 4; ++j) { NORM_LDX(i + 1); if (has_prev) mn[j] = __builtin_nontemporal_load((const u32x2*)(H + (size_t)(r + 1) * DM + lane * 4 + 256 * j)); }
;             }
.LBB0_1137:
	global_load_dwordx4 v[68:71], v[114:115], off offset:1024
	v_mov_b32_e32 v102, v126
	v_mov_b32_e32 v103, v127
	s_and_b64 vcc, exec, s[42:43]
	v_mov_b64_e32 v[118:119], v[110:111]
	s_cbranch_vccz .LBB0_1117
	s_branch .LBB0_1118

; #define NORM_LDX(rowoff) do { if (n == 0) xn[j] = *(const f32x4*)(xsrc + (size_t)(rowoff) * DM + lane * 4 + 256 * j); \
;             else xr[j] = __builtin_nontemporal_load((const u32x2*)(X + (size_t)(r0 + (rowoff)) * DM + lane * 4 + 256 * j)); } while (0)
; DI void phase_norm(ArgsP AP, int n, bool dry) {
;     ...
;             if (i + 1 < nrows) {
; #pragma unroll
;                 for (int j = 0; j < 4; ++j) { NORM_LDX(i + 1); if (has_prev) mn[j] = __builtin_nontemporal_load((const u32x2*)(H + (size_t)(r + 1) * DM + lane * 4 + 256 * j)); }
;             }
.LBB0_1139:
	global_load_dwordx4 v[72:75], v[114:115], off offset:2048
	v_mov_b32_e32 v104, v128
	v_mov_b32_e32 v105, v129
	s_and_b64 vcc, exec, s[42:43]
	v_mov_b64_e32 v[120:121], v[108:109]
	s_cbranch_vccz .LBB0_1121
	s_branch .LBB0_1122

; #define NORM_LDX(rowoff) do { if (n == 0) xn[j] = *(const f32x4*)(xsrc + (size_t)(rowoff) * DM + lane * 4 + 256 * j); \
;             else xr[j] = __builtin_nontemporal_load((const u32x2*)(X + (size_t)(r0 + (rowoff)) * DM + lane * 4 + 256 * j)); } while (0)
; DI void phase_norm(ArgsP AP, int n, bool dry) {
;     ...
;             if (i + 1 < nrows) {
; #pragma unroll
;                 for (int j = 0; j < 4; ++j) { NORM_LDX(i + 1); if (has_prev) mn[j] = __builtin_nontemporal_load((const u32x2*)(H + (size_t)(r + 1) * DM + lane * 4 + 256 * j)); }
;             }
.LBB0_1141:
	global_load_dwordx4 v[76:79], v[114:115], off offset:3072
	v_mov_b32_e32 v106, v132
	v_mov_b32_e32 v107, v133
	s_and_b64 vcc, exec, s[42:43]
	v_mov_b64_e32 v[98:99], v[130:131]
	s_cbranch_vccz .LBB0_1125
	s_branch .LBB0_1126

; #define NORM_LDX(rowoff) do { if (n == 0) xn[j] = *(const f32x4*)(xsrc + (size_t)(rowoff) * DM + lane * 4 + 256 * j); \
;             else xr[j] = __builtin_nontemporal_load((const u32x2*)(X + (size_t)(r0 + (rowoff)) * DM + lane * 4 + 256 * j)); } while (0)
; DI void phase_norm(ArgsP AP, int n, bool dry) {
;     ...
; #pragma unroll
;         for (int j = 0; j < 4; ++j) { NORM_LDX(0); if (has_prev) mn[j] = __builtin_nontemporal_load((const u32x2*)(H + (size_t)r0 * DM + lane * 4 + 256 * j)); }
.LBB0_1145:
	global_load_dwordx4 v[60:63], v[68:69], off
	v_mov_b32_e32 v124, v100
	v_mov_b32_e32 v125, v101
	s_and_b64 vcc, exec, s[42:43]
	v_lshl_add_u64 v[70:71], v[84:85], 0, v[70:71]
	s_cbranch_vccz .LBB0_1094
	s_branch .LBB0_1095

; #define NORM_LDX(rowoff) do { if (n == 0) xn[j] = *(const f32x4*)(xsrc + (size_t)(rowoff) * DM + lane * 4 + 256 * j); \
;             else xr[j] = __builtin_nontemporal_load((const u32x2*)(X + (size_t)(r0 + (rowoff)) * DM + lane * 4 + 256 * j)); } while (0)
; DI void phase_norm(ArgsP AP, int n, bool dry) {
;     ...
; #pragma unroll
;         for (int j = 0; j < 4; ++j) { NORM_LDX(0); if (has_prev) mn[j] = __builtin_nontemporal_load((const u32x2*)(H + (size_t)r0 * DM + lane * 4 + 256 * j)); }
.LBB0_1147:
	global_load_dwordx4 v[56:59], v[68:69], off offset:1024
	v_mov_b32_e32 v126, v102
	v_mov_b32_e32 v127, v103
	s_and_b64 vcc, exec, s[42:43]
	s_cbranch_vccz .LBB0_1098
	s_branch .LBB0_1099

; #define NORM_LDX(rowoff) do { if (n == 0) xn[j] = *(const f32x4*)(xsrc + (size_t)(rowoff) * DM + lane * 4 + 256 * j); \
;             else xr[j] = __builtin_nontemporal_load((const u32x2*)(X + (size_t)(r0 + (rowoff)) * DM + lane * 4 + 256 * j)); } while (0)
; DI void phase_norm(ArgsP AP, int n, bool dry) {
;     ...
; #pragma unroll
;         for (int j = 0; j < 4; ++j) { NORM_LDX(0); if (has_prev) mn[j] = __builtin_nontemporal_load((const u32x2*)(H + (size_t)r0 * DM + lane * 4 + 256 * j)); }
.LBB0_1149:
	global_load_dwordx4 v[52:55], v[68:69], off offset:2048
	v_mov_b32_e32 v128, v104
	v_mov_b32_e32 v129, v105
	s_and_b64 vcc, exec, s[42:43]
	s_cbranch_vccz .LBB0_1102
	s_branch .LBB0_1103

; #define NORM_LDX(rowoff) do { if (n == 0) xn[j] = *(const f32x4*)(xsrc + (size_t)(rowoff) * DM + lane * 4 + 256 * j); \
;             else xr[j] = __builtin_nontemporal_load((const u32x2*)(X + (size_t)(r0 + (rowoff)) * DM + lane * 4 + 256 * j)); } while (0)
; DI void phase_norm(ArgsP AP, int n, bool dry) {
;     ...
; #pragma unroll
;         for (int j = 0; j < 4; ++j) { NORM_LDX(0); if (has_prev) mn[j] = __builtin_nontemporal_load((const u32x2*)(H + (size_t)r0 * DM + lane * 4 + 256 * j)); }
.LBB0_1151:
	global_load_dwordx4 v[48:51], v[68:69], off offset:3072
	v_mov_b32_e32 v132, v106
	v_mov_b32_e32 v133, v107
	s_and_b64 vcc, exec, s[18:19]
	s_cbranch_vccnz .LBB0_1106
	s_branch .LBB0_1107
